# removed the per-segment s_setprio toggling from the GEMM main loops
# speedup vs baseline: 1.0166x; 1.0022x over previous
; #define PG8_STAGE(bufoff, gbase, voff) do { _Pragma("unroll") for (int _i = 0; _i < 2; ++_i) \
;         __builtin_amdgcn_global_load_lds((const unsigned*)((const char*)(gbase) + (voff)[_i]), (LAS unsigned*)(lds + (bufoff) + ldsw + _i * 8192), 16, 0, 0); } while (0)
; #define PG8_LDA(dst, b, h) do { _Pragma("unroll") for (int m = 0; m < 4; ++m) _Pragma("unroll") for (int k = 0; k < 2; ++k) dst[m][k] = *(const LAS bf16x8*)(lds + PG8_SA(b, h) + aoff + m * 2048 + k * 1024); } while (0)
; #define PG8_LDB(dst, b, h) do { _Pragma("unroll") for (int n = 0; n < 2; ++n) _Pragma("unroll") for (int k = 0; k < 2; ++k) dst[n][k] = *(const LAS bf16x8*)(lds + PG8_SB(b, h) + boff + n * 2048 + k * 1024); } while (0)
; #define PG8_MMA(ai, bj, At, Bt) do { __builtin_amdgcn_s_setprio(1); _Pragma("unroll") for (int m = 0; m < 4; ++m) _Pragma("unroll") for (int n = 0; n < 2; ++n) _Pragma("unroll") for (int k = 0; k < 2; ++k) \
;         acc[ai][bj][m][n] = __builtin_amdgcn_mfma_f32_16x16x32_bf16(Bt[n][k], At[m][k], acc[ai][bj][m][n], 0, 0, 0); __builtin_amdgcn_s_setprio(0); } while (0)
; #define PG8_WAIT_V(n) asm volatile("s_waitcnt vmcnt(" #n ")" ::: "memory")
; #define PG8_WAIT_L(n) asm volatile("s_waitcnt lgkmcnt(" #n ")" ::: "memory")
; #define PG8_BAR __builtin_amdgcn_s_barrier()
; #define PG8_SCHED __builtin_amdgcn_sched_barrier(0)
; template <class Epi, bool GS = false>
; __device__ __forceinline__ void gemm_phase(LAS unsigned char* lds, const Gemm g, const StaticOrder& S, const Epi& E, const int tid) {
;     ...
;             const char* a2 = last ? nA : cA + (size_t)(t + 2) * kstep; const char* b2 = last ? nB : cB + (size_t)(t + 2) * kstep;
;             const char* a3 = a2 + kstep; const char* b3 = b2 + kstep;
;             PG8_LDB(B0, 0, 0); PG8_LDB(B1, 0, 1); PG8_SCHED; PG8_LDA(At, 0, 0); PG8_STAGE(PG8_SA(1, 1), a1 + hstepA, voffA);
;             PG8_WAIT_V(8); PG8_WAIT_L(0); PG8_BAR; PG8_MMA(0, 0, At, B0); PG8_MMA(0, 1, At, B1); PG8_BAR; PG8_SCHED;
;             PG8_LDA(At, 0, 1); PG8_STAGE(PG8_SB(0, 0), b2, voffB); PG8_STAGE(PG8_SB(0, 1), b2 + hstepB, voffB); PG8_STAGE(PG8_SA(0, 0), a2, voffA);
;             PG8_WAIT_V(8); PG8_WAIT_L(0); PG8_BAR; PG8_MMA(1, 0, At, B0); PG8_MMA(1, 1, At, B1); PG8_BAR; PG8_SCHED;
.LBB0_205:
	s_add_u32 s46, s44, 0xfffc0080
	s_addc_u32 s47, s45, -1
	s_add_i32 s60, 0, 0x10000
	s_cmp_eq_u32 s59, 12
	s_cselect_b32 s49, s21, s47
	s_cselect_b32 s48, s55, s46
	s_cselect_b32 s47, s17, s58
	s_cselect_b32 s46, s56, s57
	s_add_i32 s62, 0, 0x14000
	v_add_u32_e32 v156, s60, v145
	v_add_u32_e32 v164, s62, v145
	ds_read_b128 v[140:143], v156
	ds_read_b128 v[148:151], v156 offset:1024
	ds_read_b128 v[152:155], v156 offset:2048
	ds_read_b128 v[156:159], v156 offset:3072
	ds_read_b128 v[160:163], v164
	ds_read_b128 v[176:179], v164 offset:1024
	ds_read_b128 v[180:183], v164 offset:2048
	ds_read_b128 v[184:187], v164 offset:3072
	v_lshl_add_u64 v[164:165], s[44:45], 0, v[136:137]
	s_add_i32 m0, s39, 0xc000
	ds_read_b128 v[188:191], v147
	ds_read_b128 v[192:195], v147 offset:1024
	ds_read_b128 v[216:219], v147 offset:2048
	ds_read_b128 v[220:223], v147 offset:3072
	ds_read_b128 v[224:227], v147 offset:4096
	ds_read_b128 v[228:231], v147 offset:5120
	ds_read_b128 v[232:235], v147 offset:6144
	ds_read_b128 v[236:239], v147 offset:7168
	global_load_lds_dwordx4 v[164:165], off
	v_lshl_add_u64 v[164:165], s[44:45], 0, v[138:139]
	s_add_i32 m0, s39, 0xe000
	s_nop 0
	global_load_lds_dwordx4 v[164:165], off
	s_waitcnt vmcnt(8)
	s_waitcnt lgkmcnt(0)
	s_barrier
	s_waitcnt lgkmcnt(0)
	v_mfma_f32_16x16x32_bf16 v[126:129], v[140:143], v[188:191], v[126:129]
	v_mfma_f32_16x16x32_bf16 v[122:125], v[152:155], v[188:191], v[122:125]
	v_mfma_f32_16x16x32_bf16 v[118:121], v[140:143], v[216:219], v[118:121]
	v_mfma_f32_16x16x32_bf16 v[110:113], v[152:155], v[216:219], v[110:113]
	v_mfma_f32_16x16x32_bf16 v[102:105], v[140:143], v[224:227], v[102:105]
	v_mfma_f32_16x16x32_bf16 v[94:97], v[152:155], v[224:227], v[94:97]
	v_mfma_f32_16x16x32_bf16 v[86:89], v[140:143], v[232:235], v[86:89]
	v_mfma_f32_16x16x32_bf16 v[78:81], v[152:155], v[232:235], v[78:81]
	v_mfma_f32_16x16x32_bf16 v[126:129], v[148:151], v[192:195], v[126:129]
	v_mfma_f32_16x16x32_bf16 v[122:125], v[156:159], v[192:195], v[122:125]
	v_mfma_f32_16x16x32_bf16 v[118:121], v[148:151], v[220:223], v[118:121]
	v_mfma_f32_16x16x32_bf16 v[110:113], v[156:159], v[220:223], v[110:113]
	v_mfma_f32_16x16x32_bf16 v[102:105], v[148:151], v[228:231], v[102:105]
	v_mfma_f32_16x16x32_bf16 v[94:97], v[156:159], v[228:231], v[94:97]
	v_mfma_f32_16x16x32_bf16 v[86:89], v[148:151], v[236:239], v[86:89]
	v_mfma_f32_16x16x32_bf16 v[78:81], v[156:159], v[236:239], v[78:81]
	v_mfma_f32_16x16x32_bf16 v[114:117], v[160:163], v[188:191], v[114:117]
	v_mfma_f32_16x16x32_bf16 v[106:109], v[180:183], v[188:191], v[106:109]
	v_mfma_f32_16x16x32_bf16 v[98:101], v[160:163], v[216:219], v[98:101]
	v_mfma_f32_16x16x32_bf16 v[90:93], v[180:183], v[216:219], v[90:93]
	v_mfma_f32_16x16x32_bf16 v[82:85], v[160:163], v[224:227], v[82:85]
	v_mfma_f32_16x16x32_bf16 v[74:77], v[180:183], v[224:227], v[74:77]
	v_mfma_f32_16x16x32_bf16 v[70:73], v[160:163], v[232:235], v[70:73]
	v_mfma_f32_16x16x32_bf16 v[66:69], v[180:183], v[232:235], v[66:69]
	v_mfma_f32_16x16x32_bf16 v[114:117], v[176:179], v[192:195], v[114:117]
	v_mfma_f32_16x16x32_bf16 v[106:109], v[184:187], v[192:195], v[106:109]
	v_mfma_f32_16x16x32_bf16 v[98:101], v[176:179], v[220:223], v[98:101]
	v_mfma_f32_16x16x32_bf16 v[90:93], v[184:187], v[220:223], v[90:93]
	v_mfma_f32_16x16x32_bf16 v[82:85], v[176:179], v[228:231], v[82:85]
	v_mfma_f32_16x16x32_bf16 v[74:77], v[184:187], v[228:231], v[74:77]
	v_mfma_f32_16x16x32_bf16 v[70:73], v[176:179], v[236:239], v[70:73]
	v_mfma_f32_16x16x32_bf16 v[66:69], v[184:187], v[236:239], v[66:69]
	s_barrier
	s_add_i32 s60, s60, s3
	v_lshl_add_u64 v[164:165], s[46:47], 0, v[0:1]
	s_mov_b32 m0, s60
	ds_read_b128 v[188:191], v147 offset:16384
	ds_read_b128 v[192:195], v147 offset:17408
	ds_read_b128 v[216:219], v147 offset:18432
	ds_read_b128 v[220:223], v147 offset:19456
	ds_read_b128 v[224:227], v147 offset:20480
	ds_read_b128 v[228:231], v147 offset:21504
	ds_read_b128 v[232:235], v147 offset:22528
	ds_read_b128 v[236:239], v147 offset:23552
	global_load_lds_dwordx4 v[164:165], off
	s_add_i32 m0, s60, 0x2000
	s_add_u32 s60, s46, 0x40000
	v_lshl_add_u64 v[240:241], s[46:47], 0, v[130:131]
	s_addc_u32 s61, s47, 0
	s_add_i32 s62, s62, s3
	global_load_lds_dwordx4 v[240:241], off
	v_lshl_add_u64 v[242:243], s[60:61], 0, v[0:1]
	s_mov_b32 m0, s62
	v_lshl_add_u64 v[244:245], s[48:49], 0, v[132:133]
	global_load_lds_dwordx4 v[242:243], off
	v_lshl_add_u64 v[242:243], s[60:61], 0, v[130:131]
	s_add_i32 m0, s62, 0x2000
	s_nop 0
	global_load_lds_dwordx4 v[242:243], off
	v_lshl_add_u64 v[242:243], s[48:49], 0, v[134:135]
	s_mov_b32 m0, s39
	s_nop 0
	global_load_lds_dwordx4 v[242:243], off
	s_mov_b32 m0, s41
	s_nop 0
	global_load_lds_dwordx4 v[244:245], off
	s_waitcnt vmcnt(8)
	s_waitcnt lgkmcnt(0)
	s_barrier
; #define PG8_STAGE(bufoff, gbase, voff) do { _Pragma("unroll") for (int _i = 0; _i < 2; ++_i) \
;         __builtin_amdgcn_global_load_lds((const unsigned*)((const char*)(gbase) + (voff)[_i]), (LAS unsigned*)(lds + (bufoff) + ldsw + _i * 8192), 16, 0, 0); } while (0)
; #define PG8_LDA(dst, b, h) do { _Pragma("unroll") for (int m = 0; m < 4; ++m) _Pragma("unroll") for (int k = 0; k < 2; ++k) dst[m][k] = *(const LAS bf16x8*)(lds + PG8_SA(b, h) + aoff + m * 2048 + k * 1024); } while (0)
; #define PG8_LDB(dst, b, h) do { _Pragma("unroll") for (int n = 0; n < 2; ++n) _Pragma("unroll") for (int k = 0; k < 2; ++k) dst[n][k] = *(const LAS bf16x8*)(lds + PG8_SB(b, h) + boff + n * 2048 + k * 1024); } while (0)
; #define PG8_MMA(ai, bj, At, Bt) do { __builtin_amdgcn_s_setprio(1); _Pragma("unroll") for (int m = 0; m < 4; ++m) _Pragma("unroll") for (int n = 0; n < 2; ++n) _Pragma("unroll") for (int k = 0; k < 2; ++k) \
;         acc[ai][bj][m][n] = __builtin_amdgcn_mfma_f32_16x16x32_bf16(Bt[n][k], At[m][k], acc[ai][bj][m][n], 0, 0, 0); __builtin_amdgcn_s_setprio(0); } while (0)
; #define PG8_WAIT_V(n) asm volatile("s_waitcnt vmcnt(" #n ")" ::: "memory")
; #define PG8_WAIT_L(n) asm volatile("s_waitcnt lgkmcnt(" #n ")" ::: "memory")
; #define PG8_BAR __builtin_amdgcn_s_barrier()
; #define PG8_SCHED __builtin_amdgcn_sched_barrier(0)
; template <class Epi, bool GS = false>
; __device__ __forceinline__ void gemm_phase(LAS unsigned char* lds, const Gemm g, const StaticOrder& S, const Epi& E, const int tid) {
;     ...
;             PG8_WAIT_V(8); PG8_WAIT_L(0); PG8_BAR; PG8_MMA(1, 0, At, B0); PG8_MMA(1, 1, At, B1); PG8_BAR; PG8_SCHED;
;             PG8_LDB(B0, 1, 0); PG8_LDB(B1, 1, 1); PG8_SCHED; PG8_LDA(At, 1, 0); PG8_STAGE(PG8_SA(0, 1), a2 + hstepA, voffA);
;             PG8_WAIT_V(8); PG8_WAIT_L(0); PG8_BAR; PG8_MMA(0, 0, At, B0); PG8_MMA(0, 1, At, B1); PG8_BAR; PG8_SCHED;
;             PG8_LDA(At, 1, 1); PG8_STAGE(PG8_SB(1, 0), b3, voffB); PG8_STAGE(PG8_SB(1, 1), b3 + hstepB, voffB); PG8_STAGE(PG8_SA(1, 0), a3, voffA);
	s_waitcnt lgkmcnt(0)
	v_mfma_f32_16x16x32_bf16 v[62:65], v[140:143], v[188:191], v[62:65]
	v_mfma_f32_16x16x32_bf16 v[58:61], v[152:155], v[188:191], v[58:61]
	v_mfma_f32_16x16x32_bf16 v[54:57], v[140:143], v[216:219], v[54:57]
	v_mfma_f32_16x16x32_bf16 v[46:49], v[152:155], v[216:219], v[46:49]
	v_mfma_f32_16x16x32_bf16 v[38:41], v[140:143], v[224:227], v[38:41]
	v_mfma_f32_16x16x32_bf16 v[30:33], v[152:155], v[224:227], v[30:33]
	v_mfma_f32_16x16x32_bf16 v[22:25], v[140:143], v[232:235], v[22:25]
	v_mfma_f32_16x16x32_bf16 v[14:17], v[152:155], v[232:235], v[14:17]
	v_mfma_f32_16x16x32_bf16 v[62:65], v[148:151], v[192:195], v[62:65]
	v_mfma_f32_16x16x32_bf16 v[58:61], v[156:159], v[192:195], v[58:61]
	v_mfma_f32_16x16x32_bf16 v[54:57], v[148:151], v[220:223], v[54:57]
	v_mfma_f32_16x16x32_bf16 v[46:49], v[156:159], v[220:223], v[46:49]
	v_mfma_f32_16x16x32_bf16 v[38:41], v[148:151], v[228:231], v[38:41]
	v_mfma_f32_16x16x32_bf16 v[30:33], v[156:159], v[228:231], v[30:33]
	v_mfma_f32_16x16x32_bf16 v[22:25], v[148:151], v[236:239], v[22:25]
	v_mfma_f32_16x16x32_bf16 v[14:17], v[156:159], v[236:239], v[14:17]
	v_mfma_f32_16x16x32_bf16 v[50:53], v[160:163], v[188:191], v[50:53]
	v_mfma_f32_16x16x32_bf16 v[42:45], v[180:183], v[188:191], v[42:45]
	v_mfma_f32_16x16x32_bf16 v[34:37], v[160:163], v[216:219], v[34:37]
	v_mfma_f32_16x16x32_bf16 v[26:29], v[180:183], v[216:219], v[26:29]
	v_mfma_f32_16x16x32_bf16 v[18:21], v[160:163], v[224:227], v[18:21]
	v_mfma_f32_16x16x32_bf16 v[10:13], v[180:183], v[224:227], v[10:13]
	v_mfma_f32_16x16x32_bf16 v[6:9], v[160:163], v[232:235], v[6:9]
	v_mfma_f32_16x16x32_bf16 v[2:5], v[180:183], v[232:235], v[2:5]
	v_mfma_f32_16x16x32_bf16 v[50:53], v[176:179], v[192:195], v[50:53]
	v_mfma_f32_16x16x32_bf16 v[42:45], v[184:187], v[192:195], v[42:45]
	v_mfma_f32_16x16x32_bf16 v[34:37], v[176:179], v[220:223], v[34:37]
	v_mfma_f32_16x16x32_bf16 v[26:29], v[184:187], v[220:223], v[26:29]
	v_mfma_f32_16x16x32_bf16 v[18:21], v[176:179], v[228:231], v[18:21]
	v_mfma_f32_16x16x32_bf16 v[10:13], v[184:187], v[228:231], v[10:13]
	v_mfma_f32_16x16x32_bf16 v[6:9], v[176:179], v[236:239], v[6:9]
	v_mfma_f32_16x16x32_bf16 v[2:5], v[184:187], v[236:239], v[2:5]
	s_barrier
	s_add_i32 s60, 0, 0x18000
	s_add_i32 s61, 0, 0x1c000
	v_add_u32_e32 v156, s60, v145
	v_add_u32_e32 v169, s61, v145
	ds_read_b128 v[140:143], v156
	ds_read_b128 v[148:151], v156 offset:1024
	ds_read_b128 v[152:155], v156 offset:2048
	ds_read_b128 v[156:159], v156 offset:3072
	ds_read_b128 v[160:163], v169
	ds_read_b128 v[176:179], v169 offset:1024
	ds_read_b128 v[180:183], v169 offset:2048
	ds_read_b128 v[184:187], v169 offset:3072
	s_add_u32 s48, s48, 0x40000
	s_addc_u32 s49, s49, 0
	s_mov_b32 m0, s50
	v_lshl_add_u64 v[246:247], s[48:49], 0, v[134:135]
	ds_read_b128 v[188:191], v147 offset:32768
	ds_read_b128 v[192:195], v147 offset:33792
	ds_read_b128 v[216:219], v147 offset:34816
	ds_read_b128 v[220:223], v147 offset:35840
	ds_read_b128 v[224:227], v147 offset:36864
	ds_read_b128 v[228:231], v147 offset:37888
	ds_read_b128 v[232:235], v147 offset:38912
	ds_read_b128 v[236:239], v147 offset:39936
	global_load_lds_dwordx4 v[246:247], off
	v_lshl_add_u64 v[246:247], s[48:49], 0, v[132:133]
	s_mov_b32 m0, s51
	s_nop 0
	global_load_lds_dwordx4 v[246:247], off
	s_waitcnt vmcnt(8)
	s_waitcnt lgkmcnt(0)
	s_barrier
	s_waitcnt lgkmcnt(0)
	v_mfma_f32_16x16x32_bf16 v[126:129], v[140:143], v[188:191], v[126:129]
	v_mfma_f32_16x16x32_bf16 v[122:125], v[152:155], v[188:191], v[122:125]
	v_mfma_f32_16x16x32_bf16 v[118:121], v[140:143], v[216:219], v[118:121]
	v_mfma_f32_16x16x32_bf16 v[110:113], v[152:155], v[216:219], v[110:113]
	v_mfma_f32_16x16x32_bf16 v[102:105], v[140:143], v[224:227], v[102:105]
	v_mfma_f32_16x16x32_bf16 v[94:97], v[152:155], v[224:227], v[94:97]
	v_mfma_f32_16x16x32_bf16 v[86:89], v[140:143], v[232:235], v[86:89]
	v_mfma_f32_16x16x32_bf16 v[78:81], v[152:155], v[232:235], v[78:81]
	v_mfma_f32_16x16x32_bf16 v[126:129], v[148:151], v[192:195], v[126:129]
	v_mfma_f32_16x16x32_bf16 v[122:125], v[156:159], v[192:195], v[122:125]
	v_mfma_f32_16x16x32_bf16 v[118:121], v[148:151], v[220:223], v[118:121]
	v_mfma_f32_16x16x32_bf16 v[110:113], v[156:159], v[220:223], v[110:113]
	v_mfma_f32_16x16x32_bf16 v[102:105], v[148:151], v[228:231], v[102:105]
	v_mfma_f32_16x16x32_bf16 v[94:97], v[156:159], v[228:231], v[94:97]
	v_mfma_f32_16x16x32_bf16 v[86:89], v[148:151], v[236:239], v[86:89]
	v_mfma_f32_16x16x32_bf16 v[78:81], v[156:159], v[236:239], v[78:81]
	v_mfma_f32_16x16x32_bf16 v[114:117], v[160:163], v[188:191], v[114:117]
	v_mfma_f32_16x16x32_bf16 v[106:109], v[180:183], v[188:191], v[106:109]
	v_mfma_f32_16x16x32_bf16 v[98:101], v[160:163], v[216:219], v[98:101]
	v_mfma_f32_16x16x32_bf16 v[90:93], v[180:183], v[216:219], v[90:93]
	v_mfma_f32_16x16x32_bf16 v[82:85], v[160:163], v[224:227], v[82:85]
	v_mfma_f32_16x16x32_bf16 v[74:77], v[180:183], v[224:227], v[74:77]
	v_mfma_f32_16x16x32_bf16 v[70:73], v[160:163], v[232:235], v[70:73]
	v_mfma_f32_16x16x32_bf16 v[66:69], v[180:183], v[232:235], v[66:69]
	v_mfma_f32_16x16x32_bf16 v[114:117], v[176:179], v[192:195], v[114:117]
	v_mfma_f32_16x16x32_bf16 v[106:109], v[184:187], v[192:195], v[106:109]
	v_mfma_f32_16x16x32_bf16 v[98:101], v[176:179], v[220:223], v[98:101]
	v_mfma_f32_16x16x32_bf16 v[90:93], v[184:187], v[220:223], v[90:93]
	v_mfma_f32_16x16x32_bf16 v[82:85], v[176:179], v[228:231], v[82:85]
	v_mfma_f32_16x16x32_bf16 v[74:77], v[184:187], v[228:231], v[74:77]
	v_mfma_f32_16x16x32_bf16 v[70:73], v[176:179], v[236:239], v[70:73]
	v_mfma_f32_16x16x32_bf16 v[66:69], v[184:187], v[236:239], v[66:69]
	s_barrier
; #define PG8_STAGE(bufoff, gbase, voff) do { _Pragma("unroll") for (int _i = 0; _i < 2; ++_i) \
;         __builtin_amdgcn_global_load_lds((const unsigned*)((const char*)(gbase) + (voff)[_i]), (LAS unsigned*)(lds + (bufoff) + ldsw + _i * 8192), 16, 0, 0); } while (0)
; #define PG8_LDA(dst, b, h) do { _Pragma("unroll") for (int m = 0; m < 4; ++m) _Pragma("unroll") for (int k = 0; k < 2; ++k) dst[m][k] = *(const LAS bf16x8*)(lds + PG8_SA(b, h) + aoff + m * 2048 + k * 1024); } while (0)
; #define PG8_MMA(ai, bj, At, Bt) do { __builtin_amdgcn_s_setprio(1); _Pragma("unroll") for (int m = 0; m < 4; ++m) _Pragma("unroll") for (int n = 0; n < 2; ++n) _Pragma("unroll") for (int k = 0; k < 2; ++k) \
;         acc[ai][bj][m][n] = __builtin_amdgcn_mfma_f32_16x16x32_bf16(Bt[n][k], At[m][k], acc[ai][bj][m][n], 0, 0, 0); __builtin_amdgcn_s_setprio(0); } while (0)
; #define PG8_WAIT_V(n) asm volatile("s_waitcnt vmcnt(" #n ")" ::: "memory")
; #define PG8_WAIT_L(n) asm volatile("s_waitcnt lgkmcnt(" #n ")" ::: "memory")
; #define PG8_BAR __builtin_amdgcn_s_barrier()
; #define PG8_SCHED __builtin_amdgcn_sched_barrier(0)
; template <class Epi, bool GS = false>
; __device__ __forceinline__ void gemm_phase(LAS unsigned char* lds, const Gemm g, const StaticOrder& S, const Epi& E, const int tid) {
;     ...
;             PG8_LDA(At, 1, 1); PG8_STAGE(PG8_SB(1, 0), b3, voffB); PG8_STAGE(PG8_SB(1, 1), b3 + hstepB, voffB); PG8_STAGE(PG8_SA(1, 0), a3, voffA);
;             PG8_WAIT_V(8); PG8_WAIT_L(0); PG8_BAR; PG8_MMA(1, 0, At, B0); PG8_MMA(1, 1, At, B1); PG8_BAR; PG8_SCHED;
	s_add_i32 s48, s60, s3
	v_lshl_add_u64 v[164:165], v[164:165], 0, s[0:1]
	s_mov_b32 m0, s48
	ds_read_b128 v[188:191], v147 offset:49152
	ds_read_b128 v[192:195], v147 offset:50176
	ds_read_b128 v[216:219], v147 offset:51200
	ds_read_b128 v[220:223], v147 offset:52224
	ds_read_b128 v[224:227], v147 offset:53248
	ds_read_b128 v[228:231], v147 offset:54272
	ds_read_b128 v[232:235], v147 offset:55296
	ds_read_b128 v[236:239], v147 offset:56320
	global_load_lds_dwordx4 v[164:165], off
	s_add_i32 m0, s48, 0x2000
	s_add_u32 s46, s46, 0x40080
	v_lshl_add_u64 v[164:165], v[240:241], 0, s[0:1]
	s_addc_u32 s47, s47, 0
	s_add_i32 s48, s61, s3
	global_load_lds_dwordx4 v[164:165], off
	v_lshl_add_u64 v[164:165], s[46:47], 0, v[0:1]
	s_mov_b32 m0, s48
	s_nop 0
	global_load_lds_dwordx4 v[164:165], off
	v_lshl_add_u64 v[164:165], s[46:47], 0, v[130:131]
	s_add_i32 m0, s48, 0x2000
	s_nop 0
	global_load_lds_dwordx4 v[164:165], off
	v_lshl_add_u64 v[164:165], v[242:243], 0, s[0:1]
	s_mov_b32 m0, s52
	s_nop 0
	global_load_lds_dwordx4 v[164:165], off
	v_lshl_add_u64 v[164:165], v[244:245], 0, s[0:1]
	s_mov_b32 m0, s53
	s_nop 0
	global_load_lds_dwordx4 v[164:165], off
	s_waitcnt vmcnt(8)
	s_waitcnt lgkmcnt(0)
	s_barrier
	s_waitcnt lgkmcnt(0)
	v_mfma_f32_16x16x32_bf16 v[62:65], v[140:143], v[188:191], v[62:65]
	v_mfma_f32_16x16x32_bf16 v[58:61], v[152:155], v[188:191], v[58:61]
	v_mfma_f32_16x16x32_bf16 v[54:57], v[140:143], v[216:219], v[54:57]
	v_mfma_f32_16x16x32_bf16 v[46:49], v[152:155], v[216:219], v[46:49]
	v_mfma_f32_16x16x32_bf16 v[38:41], v[140:143], v[224:227], v[38:41]
	v_mfma_f32_16x16x32_bf16 v[30:33], v[152:155], v[224:227], v[30:33]
	v_mfma_f32_16x16x32_bf16 v[22:25], v[140:143], v[232:235], v[22:25]
	v_mfma_f32_16x16x32_bf16 v[14:17], v[152:155], v[232:235], v[14:17]
	v_mfma_f32_16x16x32_bf16 v[62:65], v[148:151], v[192:195], v[62:65]
	v_mfma_f32_16x16x32_bf16 v[58:61], v[156:159], v[192:195], v[58:61]
	v_mfma_f32_16x16x32_bf16 v[54:57], v[148:151], v[220:223], v[54:57]
	v_mfma_f32_16x16x32_bf16 v[46:49], v[156:159], v[220:223], v[46:49]
	v_mfma_f32_16x16x32_bf16 v[38:41], v[148:151], v[228:231], v[38:41]
	v_mfma_f32_16x16x32_bf16 v[30:33], v[156:159], v[228:231], v[30:33]
	v_mfma_f32_16x16x32_bf16 v[22:25], v[148:151], v[236:239], v[22:25]
	v_mfma_f32_16x16x32_bf16 v[14:17], v[156:159], v[236:239], v[14:17]
	v_mfma_f32_16x16x32_bf16 v[50:53], v[160:163], v[188:191], v[50:53]
	v_mfma_f32_16x16x32_bf16 v[42:45], v[180:183], v[188:191], v[42:45]
	v_mfma_f32_16x16x32_bf16 v[34:37], v[160:163], v[216:219], v[34:37]
	v_mfma_f32_16x16x32_bf16 v[26:29], v[180:183], v[216:219], v[26:29]
	v_mfma_f32_16x16x32_bf16 v[18:21], v[160:163], v[224:227], v[18:21]
	v_mfma_f32_16x16x32_bf16 v[10:13], v[180:183], v[224:227], v[10:13]
	v_mfma_f32_16x16x32_bf16 v[6:9], v[160:163], v[232:235], v[6:9]
	v_mfma_f32_16x16x32_bf16 v[2:5], v[180:183], v[232:235], v[2:5]
	v_mfma_f32_16x16x32_bf16 v[50:53], v[176:179], v[192:195], v[50:53]
	v_mfma_f32_16x16x32_bf16 v[42:45], v[184:187], v[192:195], v[42:45]
	v_mfma_f32_16x16x32_bf16 v[34:37], v[176:179], v[220:223], v[34:37]
	v_mfma_f32_16x16x32_bf16 v[26:29], v[184:187], v[220:223], v[26:29]
	v_mfma_f32_16x16x32_bf16 v[18:21], v[176:179], v[228:231], v[18:21]
	v_mfma_f32_16x16x32_bf16 v[10:13], v[184:187], v[228:231], v[10:13]
	v_mfma_f32_16x16x32_bf16 v[6:9], v[176:179], v[236:239], v[6:9]
	v_mfma_f32_16x16x32_bf16 v[2:5], v[184:187], v[236:239], v[2:5]
	s_barrier
	s_add_i32 s59, s59, 2
	s_add_u32 s44, s44, 0x100
	s_addc_u32 s45, s45, 0
	s_add_u32 s57, s57, 0x100
	s_addc_u32 s58, s58, 0
	s_cmp_gt_u32 s59, 13
	s_cbranch_scc0 .LBB0_205
	s_and_b64 vcc, exec, s[14:15]
	s_cbranch_vccz .LBB0_208
	s_barrier

; #define PG8_STAGE(bufoff, gbase, voff) do { _Pragma("unroll") for (int _i = 0; _i < 2; ++_i) \
;         __builtin_amdgcn_global_load_lds((const unsigned*)((const char*)(gbase) + (voff)[_i]), (LAS unsigned*)(lds + (bufoff) + ldsw + _i * 8192), 16, 0, 0); } while (0)
; #define PG8_LDA(dst, b, h) do { _Pragma("unroll") for (int m = 0; m < 4; ++m) _Pragma("unroll") for (int k = 0; k < 2; ++k) dst[m][k] = *(const LAS bf16x8*)(lds + PG8_SA(b, h) + aoff + m * 2048 + k * 1024); } while (0)
; #define PG8_LDB(dst, b, h) do { _Pragma("unroll") for (int n = 0; n < 2; ++n) _Pragma("unroll") for (int k = 0; k < 2; ++k) dst[n][k] = *(const LAS bf16x8*)(lds + PG8_SB(b, h) + boff + n * 2048 + k * 1024); } while (0)
; #define PG8_MMA(ai, bj, At, Bt) do { __builtin_amdgcn_s_setprio(1); _Pragma("unroll") for (int m = 0; m < 4; ++m) _Pragma("unroll") for (int n = 0; n < 2; ++n) _Pragma("unroll") for (int k = 0; k < 2; ++k) \
;         acc[ai][bj][m][n] = __builtin_amdgcn_mfma_f32_16x16x32_bf16(Bt[n][k], At[m][k], acc[ai][bj][m][n], 0, 0, 0); __builtin_amdgcn_s_setprio(0); } while (0)
; #define PG8_WAIT_V(n) asm volatile("s_waitcnt vmcnt(" #n ")" ::: "memory")
; #define PG8_WAIT_L(n) asm volatile("s_waitcnt lgkmcnt(" #n ")" ::: "memory")
; #define PG8_BAR __builtin_amdgcn_s_barrier()
; #define PG8_SCHED __builtin_amdgcn_sched_barrier(0)
; template <class Epi, bool GS = false>
; __device__ __forceinline__ void gemm_phase(LAS unsigned char* lds, const Gemm g, const StaticOrder& S, const Epi& E, const int tid) {
;     ...
;         for (int t = tg; t < tg + seg; t += 2) {
;             const bool last = (t == nt - 2);
;             const char* a1 = cA + (size_t)(t + 1) * kstep;
;             const char* a2 = last ? nA : cA + (size_t)(t + 2) * kstep; const char* b2 = last ? nB : cB + (size_t)(t + 2) * kstep;
;             const char* a3 = a2 + kstep; const char* b3 = b2 + kstep;
;             PG8_LDB(B0, 0, 0); PG8_LDB(B1, 0, 1); PG8_SCHED; PG8_LDA(At, 0, 0); PG8_STAGE(PG8_SA(1, 1), a1 + hstepA, voffA);
;             PG8_WAIT_V(8); PG8_WAIT_L(0); PG8_BAR; PG8_MMA(0, 0, At, B0); PG8_MMA(0, 1, At, B1); PG8_BAR; PG8_SCHED;
;             PG8_LDA(At, 0, 1); PG8_STAGE(PG8_SB(0, 0), b2, voffB); PG8_STAGE(PG8_SB(0, 1), b2 + hstepB, voffB); PG8_STAGE(PG8_SA(0, 0), a2, voffA);
;             PG8_WAIT_V(8); PG8_WAIT_L(0); PG8_BAR; PG8_MMA(1, 0, At, B0); PG8_MMA(1, 1, At, B1); PG8_BAR; PG8_SCHED;
.LBB0_666:
	s_add_u32 s22, s8, s4
	s_addc_u32 s23, s9, s5
	s_add_u32 s22, s22, 0x100
	s_addc_u32 s23, s23, 0
	s_add_u32 s70, s65, s4
	s_addc_u32 s71, s66, s5
	s_add_i32 s72, 0, 0x10000
	s_cmp_eq_u32 s62, s69
	s_cselect_b32 s43, s47, s23
	s_cselect_b32 s42, s46, s22
	v_add_u32_e32 v0, s72, v215
	s_cselect_b32 s23, s49, s71
	s_cselect_b32 s22, s48, s70
	s_add_i32 s73, 0, 0x14000
	ds_read_b128 v[138:141], v0
	ds_read_b128 v[142:145], v0 offset:1024
	ds_read_b128 v[146:149], v0 offset:2048
	ds_read_b128 v[150:153], v0 offset:3072
	v_add_u32_e32 v0, s73, v215
	ds_read_b128 v[154:157], v0
	ds_read_b128 v[158:161], v0 offset:1024
	ds_read_b128 v[162:165], v0 offset:2048
	ds_read_b128 v[188:191], v0 offset:3072
	v_lshl_add_u64 v[2:3], v[120:121], 0, s[4:5]
	s_add_i32 m0, s3, 0xc000
	ds_read_b128 v[192:195], v218
	ds_read_b128 v[220:223], v218 offset:1024
	ds_read_b128 v[224:227], v218 offset:2048
	ds_read_b128 v[228:231], v218 offset:3072
	ds_read_b128 v[232:235], v218 offset:4096
	ds_read_b128 v[236:239], v218 offset:5120
	ds_read_b128 v[240:243], v218 offset:6144
	ds_read_b128 v[244:247], v218 offset:7168
	global_load_lds_dwordx4 v[2:3], off
	v_lshl_add_u64 v[2:3], v[134:135], 0, s[4:5]
	s_add_i32 m0, s3, 0xe000
	s_nop 0
	global_load_lds_dwordx4 v[2:3], off
	s_waitcnt vmcnt(8)
	s_waitcnt lgkmcnt(0)
	s_barrier
	s_waitcnt lgkmcnt(0)
	v_mfma_f32_16x16x32_bf16 v[130:133], v[138:141], v[192:195], v[130:133]
	v_mfma_f32_16x16x32_bf16 v[126:129], v[146:149], v[192:195], v[126:129]
	v_mfma_f32_16x16x32_bf16 v[112:115], v[138:141], v[224:227], v[112:115]
	v_mfma_f32_16x16x32_bf16 v[108:111], v[146:149], v[224:227], v[108:111]
	v_mfma_f32_16x16x32_bf16 v[96:99], v[138:141], v[232:235], v[96:99]
	v_mfma_f32_16x16x32_bf16 v[92:95], v[146:149], v[232:235], v[92:95]
	v_mfma_f32_16x16x32_bf16 v[80:83], v[138:141], v[240:243], v[80:83]
	v_mfma_f32_16x16x32_bf16 v[76:79], v[146:149], v[240:243], v[76:79]
	v_mfma_f32_16x16x32_bf16 v[130:133], v[142:145], v[220:223], v[130:133]
	v_mfma_f32_16x16x32_bf16 v[126:129], v[150:153], v[220:223], v[126:129]
	v_mfma_f32_16x16x32_bf16 v[112:115], v[142:145], v[228:231], v[112:115]
	v_mfma_f32_16x16x32_bf16 v[108:111], v[150:153], v[228:231], v[108:111]
	v_mfma_f32_16x16x32_bf16 v[96:99], v[142:145], v[236:239], v[96:99]
	v_mfma_f32_16x16x32_bf16 v[92:95], v[150:153], v[236:239], v[92:95]
	v_mfma_f32_16x16x32_bf16 v[80:83], v[142:145], v[244:247], v[80:83]
	v_mfma_f32_16x16x32_bf16 v[76:79], v[150:153], v[244:247], v[76:79]
	v_mfma_f32_16x16x32_bf16 v[122:125], v[154:157], v[192:195], v[122:125]
	v_mfma_f32_16x16x32_bf16 v[116:119], v[162:165], v[192:195], v[116:119]
	v_mfma_f32_16x16x32_bf16 v[104:107], v[154:157], v[224:227], v[104:107]
	v_mfma_f32_16x16x32_bf16 v[100:103], v[162:165], v[224:227], v[100:103]
	v_mfma_f32_16x16x32_bf16 v[88:91], v[154:157], v[232:235], v[88:91]
	v_mfma_f32_16x16x32_bf16 v[84:87], v[162:165], v[232:235], v[84:87]
	v_mfma_f32_16x16x32_bf16 v[72:75], v[154:157], v[240:243], v[72:75]
	v_mfma_f32_16x16x32_bf16 v[68:71], v[162:165], v[240:243], v[68:71]
	v_mfma_f32_16x16x32_bf16 v[122:125], v[158:161], v[220:223], v[122:125]
	v_mfma_f32_16x16x32_bf16 v[116:119], v[188:191], v[220:223], v[116:119]
	v_mfma_f32_16x16x32_bf16 v[104:107], v[158:161], v[228:231], v[104:107]
	v_mfma_f32_16x16x32_bf16 v[100:103], v[188:191], v[228:231], v[100:103]
	v_mfma_f32_16x16x32_bf16 v[88:91], v[158:161], v[236:239], v[88:91]
	v_mfma_f32_16x16x32_bf16 v[84:87], v[188:191], v[236:239], v[84:87]
	v_mfma_f32_16x16x32_bf16 v[72:75], v[158:161], v[244:247], v[72:75]
	v_mfma_f32_16x16x32_bf16 v[68:71], v[188:191], v[244:247], v[68:71]
	s_barrier
	s_add_i32 s70, s72, s2
	v_lshl_add_u64 v[248:249], s[22:23], 0, v[178:179]
	s_mov_b32 m0, s70
	ds_read_b128 v[192:195], v218 offset:16384
	ds_read_b128 v[220:223], v218 offset:17408
	ds_read_b128 v[224:227], v218 offset:18432
	ds_read_b128 v[228:231], v218 offset:19456
	ds_read_b128 v[232:235], v218 offset:20480
	ds_read_b128 v[236:239], v218 offset:21504
	ds_read_b128 v[240:243], v218 offset:22528
	ds_read_b128 v[244:247], v218 offset:23552
	global_load_lds_dwordx4 v[248:249], off
	s_add_i32 m0, s70, 0x2000
	s_add_u32 s70, s22, 0xc0000
	v_lshl_add_u64 v[250:251], s[22:23], 0, v[182:183]
	s_addc_u32 s71, s23, 0
	s_add_i32 s72, s73, s2
	global_load_lds_dwordx4 v[250:251], off
	v_lshl_add_u64 v[2:3], s[70:71], 0, v[178:179]
	s_mov_b32 m0, s72
	v_lshl_add_u64 v[170:171], s[42:43], 0, v[176:177]
	global_load_lds_dwordx4 v[2:3], off
	v_lshl_add_u64 v[2:3], s[70:71], 0, v[182:183]
	s_add_i32 m0, s72, 0x2000
	v_lshl_add_u64 v[172:173], s[42:43], 0, v[180:181]
	global_load_lds_dwordx4 v[2:3], off
	s_mov_b32 m0, s3
	s_nop 0
	global_load_lds_dwordx4 v[170:171], off
	s_mov_b32 m0, s37
	s_nop 0
	global_load_lds_dwordx4 v[172:173], off
	s_waitcnt vmcnt(8)
	s_waitcnt lgkmcnt(0)
	s_barrier
; #define PG8_STAGE(bufoff, gbase, voff) do { _Pragma("unroll") for (int _i = 0; _i < 2; ++_i) \
;         __builtin_amdgcn_global_load_lds((const unsigned*)((const char*)(gbase) + (voff)[_i]), (LAS unsigned*)(lds + (bufoff) + ldsw + _i * 8192), 16, 0, 0); } while (0)
; #define PG8_LDA(dst, b, h) do { _Pragma("unroll") for (int m = 0; m < 4; ++m) _Pragma("unroll") for (int k = 0; k < 2; ++k) dst[m][k] = *(const LAS bf16x8*)(lds + PG8_SA(b, h) + aoff + m * 2048 + k * 1024); } while (0)
; #define PG8_LDB(dst, b, h) do { _Pragma("unroll") for (int n = 0; n < 2; ++n) _Pragma("unroll") for (int k = 0; k < 2; ++k) dst[n][k] = *(const LAS bf16x8*)(lds + PG8_SB(b, h) + boff + n * 2048 + k * 1024); } while (0)
; #define PG8_MMA(ai, bj, At, Bt) do { __builtin_amdgcn_s_setprio(1); _Pragma("unroll") for (int m = 0; m < 4; ++m) _Pragma("unroll") for (int n = 0; n < 2; ++n) _Pragma("unroll") for (int k = 0; k < 2; ++k) \
;         acc[ai][bj][m][n] = __builtin_amdgcn_mfma_f32_16x16x32_bf16(Bt[n][k], At[m][k], acc[ai][bj][m][n], 0, 0, 0); __builtin_amdgcn_s_setprio(0); } while (0)
; #define PG8_WAIT_V(n) asm volatile("s_waitcnt vmcnt(" #n ")" ::: "memory")
; #define PG8_WAIT_L(n) asm volatile("s_waitcnt lgkmcnt(" #n ")" ::: "memory")
; #define PG8_BAR __builtin_amdgcn_s_barrier()
; #define PG8_SCHED __builtin_amdgcn_sched_barrier(0)
; template <class Epi, bool GS = false>
; __device__ __forceinline__ void gemm_phase(LAS unsigned char* lds, const Gemm g, const StaticOrder& S, const Epi& E, const int tid) {
;     ...
;             PG8_WAIT_V(8); PG8_WAIT_L(0); PG8_BAR; PG8_MMA(0, 0, At, B0); PG8_MMA(0, 1, At, B1); PG8_BAR; PG8_SCHED;
;             PG8_LDA(At, 0, 1); PG8_STAGE(PG8_SB(0, 0), b2, voffB); PG8_STAGE(PG8_SB(0, 1), b2 + hstepB, voffB); PG8_STAGE(PG8_SA(0, 0), a2, voffA);
;             PG8_WAIT_V(8); PG8_WAIT_L(0); PG8_BAR; PG8_MMA(1, 0, At, B0); PG8_MMA(1, 1, At, B1); PG8_BAR; PG8_SCHED;
;             PG8_LDB(B0, 1, 0); PG8_LDB(B1, 1, 1); PG8_SCHED; PG8_LDA(At, 1, 0); PG8_STAGE(PG8_SA(0, 1), a2 + hstepA, voffA);
;             PG8_WAIT_V(8); PG8_WAIT_L(0); PG8_BAR; PG8_MMA(0, 0, At, B0); PG8_MMA(0, 1, At, B1); PG8_BAR; PG8_SCHED;
	s_waitcnt lgkmcnt(0)
	v_mfma_f32_16x16x32_bf16 v[64:67], v[138:141], v[192:195], v[64:67]
	v_mfma_f32_16x16x32_bf16 v[60:63], v[146:149], v[192:195], v[60:63]
	v_mfma_f32_16x16x32_bf16 v[48:51], v[138:141], v[224:227], v[48:51]
	v_mfma_f32_16x16x32_bf16 v[44:47], v[146:149], v[224:227], v[44:47]
	v_mfma_f32_16x16x32_bf16 v[32:35], v[138:141], v[232:235], v[32:35]
	v_mfma_f32_16x16x32_bf16 v[28:31], v[146:149], v[232:235], v[28:31]
	v_mfma_f32_16x16x32_bf16 v[16:19], v[138:141], v[240:243], v[16:19]
	v_mfma_f32_16x16x32_bf16 v[12:15], v[146:149], v[240:243], v[12:15]
	v_mfma_f32_16x16x32_bf16 v[64:67], v[142:145], v[220:223], v[64:67]
	v_mfma_f32_16x16x32_bf16 v[60:63], v[150:153], v[220:223], v[60:63]
	v_mfma_f32_16x16x32_bf16 v[48:51], v[142:145], v[228:231], v[48:51]
	v_mfma_f32_16x16x32_bf16 v[44:47], v[150:153], v[228:231], v[44:47]
	v_mfma_f32_16x16x32_bf16 v[32:35], v[142:145], v[236:239], v[32:35]
	v_mfma_f32_16x16x32_bf16 v[28:31], v[150:153], v[236:239], v[28:31]
	v_mfma_f32_16x16x32_bf16 v[16:19], v[142:145], v[244:247], v[16:19]
	v_mfma_f32_16x16x32_bf16 v[12:15], v[150:153], v[244:247], v[12:15]
	v_mfma_f32_16x16x32_bf16 v[56:59], v[154:157], v[192:195], v[56:59]
	v_mfma_f32_16x16x32_bf16 v[52:55], v[162:165], v[192:195], v[52:55]
	v_mfma_f32_16x16x32_bf16 v[40:43], v[154:157], v[224:227], v[40:43]
	v_mfma_f32_16x16x32_bf16 v[36:39], v[162:165], v[224:227], v[36:39]
	v_mfma_f32_16x16x32_bf16 v[24:27], v[154:157], v[232:235], v[24:27]
	v_mfma_f32_16x16x32_bf16 v[20:23], v[162:165], v[232:235], v[20:23]
	v_mfma_f32_16x16x32_bf16 v[8:11], v[154:157], v[240:243], v[8:11]
	v_mfma_f32_16x16x32_bf16 v[2:5], v[162:165], v[240:243], v[4:7]
	v_mfma_f32_16x16x32_bf16 v[56:59], v[158:161], v[220:223], v[56:59]
	v_mfma_f32_16x16x32_bf16 v[52:55], v[188:191], v[220:223], v[52:55]
	v_mfma_f32_16x16x32_bf16 v[40:43], v[158:161], v[228:231], v[40:43]
	v_mfma_f32_16x16x32_bf16 v[36:39], v[188:191], v[228:231], v[36:39]
	v_mfma_f32_16x16x32_bf16 v[24:27], v[158:161], v[236:239], v[24:27]
	v_mfma_f32_16x16x32_bf16 v[20:23], v[188:191], v[236:239], v[20:23]
	v_mfma_f32_16x16x32_bf16 v[8:11], v[158:161], v[244:247], v[8:11]
	v_mfma_f32_16x16x32_bf16 v[2:5], v[188:191], v[244:247], v[2:5]
	s_barrier
	s_add_i32 s70, 0, 0x18000
	v_add_u32_e32 v0, s70, v215
	s_add_i32 s71, 0, 0x1c000
	ds_read_b128 v[138:141], v0
	ds_read_b128 v[142:145], v0 offset:1024
	ds_read_b128 v[146:149], v0 offset:2048
	ds_read_b128 v[150:153], v0 offset:3072
	v_add_u32_e32 v0, s71, v215
	ds_read_b128 v[154:157], v0
	ds_read_b128 v[158:161], v0 offset:1024
	ds_read_b128 v[162:165], v0 offset:2048
	ds_read_b128 v[188:191], v0 offset:3072
	s_add_u32 s42, s42, 0x230000
	s_addc_u32 s43, s43, 0
	s_mov_b32 m0, s50
	v_lshl_add_u64 v[6:7], s[42:43], 0, v[176:177]
	ds_read_b128 v[192:195], v218 offset:32768
	ds_read_b128 v[220:223], v218 offset:33792
	ds_read_b128 v[224:227], v218 offset:34816
	ds_read_b128 v[228:231], v218 offset:35840
	ds_read_b128 v[232:235], v218 offset:36864
	ds_read_b128 v[236:239], v218 offset:37888
	ds_read_b128 v[240:243], v218 offset:38912
	ds_read_b128 v[244:247], v218 offset:39936
	global_load_lds_dwordx4 v[6:7], off
	v_lshl_add_u64 v[6:7], s[42:43], 0, v[180:181]
	s_mov_b32 m0, s51
	s_nop 0
	global_load_lds_dwordx4 v[6:7], off
	s_waitcnt vmcnt(8)
	s_waitcnt lgkmcnt(0)
	s_barrier
	s_waitcnt lgkmcnt(0)
	v_mfma_f32_16x16x32_bf16 v[130:133], v[138:141], v[192:195], v[130:133]
	v_mfma_f32_16x16x32_bf16 v[126:129], v[146:149], v[192:195], v[126:129]
	v_mfma_f32_16x16x32_bf16 v[112:115], v[138:141], v[224:227], v[112:115]
	v_mfma_f32_16x16x32_bf16 v[108:111], v[146:149], v[224:227], v[108:111]
	v_mfma_f32_16x16x32_bf16 v[96:99], v[138:141], v[232:235], v[96:99]
	v_mfma_f32_16x16x32_bf16 v[92:95], v[146:149], v[232:235], v[92:95]
	v_mfma_f32_16x16x32_bf16 v[80:83], v[138:141], v[240:243], v[80:83]
	v_mfma_f32_16x16x32_bf16 v[76:79], v[146:149], v[240:243], v[76:79]
	v_mfma_f32_16x16x32_bf16 v[130:133], v[142:145], v[220:223], v[130:133]
	v_mfma_f32_16x16x32_bf16 v[126:129], v[150:153], v[220:223], v[126:129]
	v_mfma_f32_16x16x32_bf16 v[112:115], v[142:145], v[228:231], v[112:115]
	v_mfma_f32_16x16x32_bf16 v[108:111], v[150:153], v[228:231], v[108:111]
	v_mfma_f32_16x16x32_bf16 v[96:99], v[142:145], v[236:239], v[96:99]
	v_mfma_f32_16x16x32_bf16 v[92:95], v[150:153], v[236:239], v[92:95]
	v_mfma_f32_16x16x32_bf16 v[80:83], v[142:145], v[244:247], v[80:83]
	v_mfma_f32_16x16x32_bf16 v[76:79], v[150:153], v[244:247], v[76:79]
	v_mfma_f32_16x16x32_bf16 v[122:125], v[154:157], v[192:195], v[122:125]
	v_mfma_f32_16x16x32_bf16 v[116:119], v[162:165], v[192:195], v[116:119]
	v_mfma_f32_16x16x32_bf16 v[104:107], v[154:157], v[224:227], v[104:107]
	v_mfma_f32_16x16x32_bf16 v[100:103], v[162:165], v[224:227], v[100:103]
	v_mfma_f32_16x16x32_bf16 v[88:91], v[154:157], v[232:235], v[88:91]
	v_mfma_f32_16x16x32_bf16 v[84:87], v[162:165], v[232:235], v[84:87]
	v_mfma_f32_16x16x32_bf16 v[72:75], v[154:157], v[240:243], v[72:75]
	v_mfma_f32_16x16x32_bf16 v[68:71], v[162:165], v[240:243], v[68:71]
	v_mfma_f32_16x16x32_bf16 v[122:125], v[158:161], v[220:223], v[122:125]
	v_mfma_f32_16x16x32_bf16 v[116:119], v[188:191], v[220:223], v[116:119]
	v_mfma_f32_16x16x32_bf16 v[104:107], v[158:161], v[228:231], v[104:107]
	v_mfma_f32_16x16x32_bf16 v[100:103], v[188:191], v[228:231], v[100:103]
	v_mfma_f32_16x16x32_bf16 v[88:91], v[158:161], v[236:239], v[88:91]
	v_mfma_f32_16x16x32_bf16 v[84:87], v[188:191], v[236:239], v[84:87]
	v_mfma_f32_16x16x32_bf16 v[72:75], v[158:161], v[244:247], v[72:75]
	v_mfma_f32_16x16x32_bf16 v[68:71], v[188:191], v[244:247], v[68:71]
	s_barrier
; #define LAS __attribute__((address_space(3)))
; #define PG8_STAGE(bufoff, gbase, voff) do { _Pragma("unroll") for (int _i = 0; _i < 2; ++_i) \
;         __builtin_amdgcn_global_load_lds((const unsigned*)((const char*)(gbase) + (voff)[_i]), (LAS unsigned*)(lds + (bufoff) + ldsw + _i * 8192), 16, 0, 0); } while (0)
; #define PG8_LDA(dst, b, h) do { _Pragma("unroll") for (int m = 0; m < 4; ++m) _Pragma("unroll") for (int k = 0; k < 2; ++k) dst[m][k] = *(const LAS bf16x8*)(lds + PG8_SA(b, h) + aoff + m * 2048 + k * 1024); } while (0)
; #define PG8_MMA(ai, bj, At, Bt) do { __builtin_amdgcn_s_setprio(1); _Pragma("unroll") for (int m = 0; m < 4; ++m) _Pragma("unroll") for (int n = 0; n < 2; ++n) _Pragma("unroll") for (int k = 0; k < 2; ++k) \
;         acc[ai][bj][m][n] = __builtin_amdgcn_mfma_f32_16x16x32_bf16(Bt[n][k], At[m][k], acc[ai][bj][m][n], 0, 0, 0); __builtin_amdgcn_s_setprio(0); } while (0)
; #define PG8_WAIT_V(n) asm volatile("s_waitcnt vmcnt(" #n ")" ::: "memory")
; #define PG8_WAIT_L(n) asm volatile("s_waitcnt lgkmcnt(" #n ")" ::: "memory")
; #define PG8_BAR __builtin_amdgcn_s_barrier()
; #define PG8_SCHED __builtin_amdgcn_sched_barrier(0)
; template <class Epi, bool GS = false>
; __device__ __forceinline__ void gemm_phase(LAS unsigned char* lds, const Gemm g, const StaticOrder& S, const Epi& E, const int tid) {
;     ...
;             PG8_LDA(At, 1, 1); PG8_STAGE(PG8_SB(1, 0), b3, voffB); PG8_STAGE(PG8_SB(1, 1), b3 + hstepB, voffB); PG8_STAGE(PG8_SA(1, 0), a3, voffA);
;             PG8_WAIT_V(8); PG8_WAIT_L(0); PG8_BAR; PG8_MMA(1, 0, At, B0); PG8_MMA(1, 1, At, B1); PG8_BAR; PG8_SCHED;
;         }
;         if constexpr (GS) {
;             const bool ds = cur.part == 0;
;             const LAS float* rt = (const LAS float*)(lds + STAGE_BYTES) + (ui >> 1) * 1024 + (tg >> 3) + (wr * 64 + fr) * 4;
; #pragma unroll
;             for (int a = 0; a < 2; ++a)
; #pragma unroll
;                 for (int m = 0; m < 4; ++m) { const float f = ds ? rt[(a * HALF + m * 16) * 4] : 1.f;
	s_add_i32 s42, s70, s2
	v_lshl_add_u64 v[6:7], v[248:249], 0, s[0:1]
	s_mov_b32 m0, s42
	ds_read_b128 v[192:195], v218 offset:49152
	ds_read_b128 v[220:223], v218 offset:50176
	ds_read_b128 v[224:227], v218 offset:51200
	ds_read_b128 v[228:231], v218 offset:52224
	ds_read_b128 v[232:235], v218 offset:53248
	ds_read_b128 v[236:239], v218 offset:54272
	ds_read_b128 v[240:243], v218 offset:55296
	ds_read_b128 v[244:247], v218 offset:56320
	global_load_lds_dwordx4 v[6:7], off
	s_add_i32 m0, s42, 0x2000
	s_add_u32 s22, s22, 0xc0080
	v_lshl_add_u64 v[6:7], v[250:251], 0, s[0:1]
	s_addc_u32 s23, s23, 0
	s_add_i32 s42, s71, s2
	global_load_lds_dwordx4 v[6:7], off
	v_lshl_add_u64 v[6:7], s[22:23], 0, v[178:179]
	s_mov_b32 m0, s42
	s_nop 0
	global_load_lds_dwordx4 v[6:7], off
	v_lshl_add_u64 v[6:7], s[22:23], 0, v[182:183]
	s_add_i32 m0, s42, 0x2000
	s_nop 0
	global_load_lds_dwordx4 v[6:7], off
	v_lshl_add_u64 v[6:7], v[170:171], 0, s[0:1]
	s_mov_b32 m0, s52
	s_nop 0
	global_load_lds_dwordx4 v[6:7], off
	v_lshl_add_u64 v[6:7], v[172:173], 0, s[0:1]
	s_mov_b32 m0, s53
	s_nop 0
	global_load_lds_dwordx4 v[6:7], off
	s_waitcnt vmcnt(8)
	s_waitcnt lgkmcnt(0)
	s_barrier
	s_waitcnt lgkmcnt(0)
	v_mfma_f32_16x16x32_bf16 v[64:67], v[138:141], v[192:195], v[64:67]
	v_mfma_f32_16x16x32_bf16 v[60:63], v[146:149], v[192:195], v[60:63]
	v_mfma_f32_16x16x32_bf16 v[48:51], v[138:141], v[224:227], v[48:51]
	v_mfma_f32_16x16x32_bf16 v[44:47], v[146:149], v[224:227], v[44:47]
	v_mfma_f32_16x16x32_bf16 v[32:35], v[138:141], v[232:235], v[32:35]
	v_mfma_f32_16x16x32_bf16 v[28:31], v[146:149], v[232:235], v[28:31]
	v_mfma_f32_16x16x32_bf16 v[16:19], v[138:141], v[240:243], v[16:19]
	v_mfma_f32_16x16x32_bf16 v[12:15], v[146:149], v[240:243], v[12:15]
	v_mfma_f32_16x16x32_bf16 v[64:67], v[142:145], v[220:223], v[64:67]
	v_mfma_f32_16x16x32_bf16 v[60:63], v[150:153], v[220:223], v[60:63]
	v_mfma_f32_16x16x32_bf16 v[48:51], v[142:145], v[228:231], v[48:51]
	v_mfma_f32_16x16x32_bf16 v[44:47], v[150:153], v[228:231], v[44:47]
	v_mfma_f32_16x16x32_bf16 v[32:35], v[142:145], v[236:239], v[32:35]
	v_mfma_f32_16x16x32_bf16 v[28:31], v[150:153], v[236:239], v[28:31]
	v_mfma_f32_16x16x32_bf16 v[16:19], v[142:145], v[244:247], v[16:19]
	v_mfma_f32_16x16x32_bf16 v[12:15], v[150:153], v[244:247], v[12:15]
	v_mfma_f32_16x16x32_bf16 v[56:59], v[154:157], v[192:195], v[56:59]
	v_mfma_f32_16x16x32_bf16 v[52:55], v[162:165], v[192:195], v[52:55]
	v_mfma_f32_16x16x32_bf16 v[40:43], v[154:157], v[224:227], v[40:43]
	v_mfma_f32_16x16x32_bf16 v[36:39], v[162:165], v[224:227], v[36:39]
	v_mfma_f32_16x16x32_bf16 v[24:27], v[154:157], v[232:235], v[24:27]
	v_mfma_f32_16x16x32_bf16 v[20:23], v[162:165], v[232:235], v[20:23]
	v_mfma_f32_16x16x32_bf16 v[6:9], v[154:157], v[240:243], v[8:11]
	v_mfma_f32_16x16x32_bf16 v[2:5], v[162:165], v[240:243], v[2:5]
	v_mfma_f32_16x16x32_bf16 v[56:59], v[158:161], v[220:223], v[56:59]
	v_mfma_f32_16x16x32_bf16 v[52:55], v[188:191], v[220:223], v[52:55]
	v_mfma_f32_16x16x32_bf16 v[40:43], v[158:161], v[228:231], v[40:43]
	v_mfma_f32_16x16x32_bf16 v[36:39], v[188:191], v[228:231], v[36:39]
	v_mfma_f32_16x16x32_bf16 v[24:27], v[158:161], v[236:239], v[24:27]
	v_mfma_f32_16x16x32_bf16 v[20:23], v[188:191], v[236:239], v[20:23]
	v_mfma_f32_16x16x32_bf16 v[8:11], v[158:161], v[244:247], v[6:9]
	v_mfma_f32_16x16x32_bf16 v[4:7], v[188:191], v[244:247], v[2:5]
	s_barrier
	s_add_u32 s4, s4, 0x100
	s_addc_u32 s5, s5, 0
	s_add_i32 s22, s69, 2
	s_cmp_ge_u32 s69, s61
	s_mov_b32 s69, s22
	s_cbranch_scc0 .LBB0_666
	s_lshr_b32 s22, s68, 1
	v_mov_b32_e32 v136, 1.0
	s_and_b64 vcc, exec, s[16:17]
	v_mov_b32_e32 v0, 1.0
	s_cbranch_vccnz .LBB0_674
	v_cndmask_b32_e64 v2, 0, 1, s[16:17]
	v_cmp_ne_u32_e64 s[4:5], 1, v2
	s_andn2_b64 vcc, exec, s[16:17]
	s_cbranch_vccz .LBB0_675

; #define PG8_STAGE(bufoff, gbase, voff) do { _Pragma("unroll") for (int _i = 0; _i < 2; ++_i) \
;         __builtin_amdgcn_global_load_lds((const unsigned*)((const char*)(gbase) + (voff)[_i]), (LAS unsigned*)(lds + (bufoff) + ldsw + _i * 8192), 16, 0, 0); } while (0)
; #define PG8_LDA(dst, b, h) do { _Pragma("unroll") for (int m = 0; m < 4; ++m) _Pragma("unroll") for (int k = 0; k < 2; ++k) dst[m][k] = *(const LAS bf16x8*)(lds + PG8_SA(b, h) + aoff + m * 2048 + k * 1024); } while (0)
; #define PG8_LDB(dst, b, h) do { _Pragma("unroll") for (int n = 0; n < 2; ++n) _Pragma("unroll") for (int k = 0; k < 2; ++k) dst[n][k] = *(const LAS bf16x8*)(lds + PG8_SB(b, h) + boff + n * 2048 + k * 1024); } while (0)
; #define PG8_MMA(ai, bj, At, Bt) do { __builtin_amdgcn_s_setprio(1); _Pragma("unroll") for (int m = 0; m < 4; ++m) _Pragma("unroll") for (int n = 0; n < 2; ++n) _Pragma("unroll") for (int k = 0; k < 2; ++k) \
;         acc[ai][bj][m][n] = __builtin_amdgcn_mfma_f32_16x16x32_bf16(Bt[n][k], At[m][k], acc[ai][bj][m][n], 0, 0, 0); __builtin_amdgcn_s_setprio(0); } while (0)
; #define PG8_WAIT_V(n) asm volatile("s_waitcnt vmcnt(" #n ")" ::: "memory")
; #define PG8_WAIT_L(n) asm volatile("s_waitcnt lgkmcnt(" #n ")" ::: "memory")
; #define PG8_BAR __builtin_amdgcn_s_barrier()
; #define PG8_SCHED __builtin_amdgcn_sched_barrier(0)
; template <class Epi, bool GS = false>
; __device__ __forceinline__ void gemm_phase(LAS unsigned char* lds, const Gemm g, const StaticOrder& S, const Epi& E, const int tid) {
;     ...
;         for (int t = tg; t < tg + seg; t += 2) {
;             const bool last = (t == nt - 2);
;             const char* a1 = cA + (size_t)(t + 1) * kstep;
;             const char* a2 = last ? nA : cA + (size_t)(t + 2) * kstep; const char* b2 = last ? nB : cB + (size_t)(t + 2) * kstep;
;             const char* a3 = a2 + kstep; const char* b3 = b2 + kstep;
;             PG8_LDB(B0, 0, 0); PG8_LDB(B1, 0, 1); PG8_SCHED; PG8_LDA(At, 0, 0); PG8_STAGE(PG8_SA(1, 1), a1 + hstepA, voffA);
;             PG8_WAIT_V(8); PG8_WAIT_L(0); PG8_BAR; PG8_MMA(0, 0, At, B0); PG8_MMA(0, 1, At, B1); PG8_BAR; PG8_SCHED;
;             PG8_LDA(At, 0, 1); PG8_STAGE(PG8_SB(0, 0), b2, voffB); PG8_STAGE(PG8_SB(0, 1), b2 + hstepB, voffB); PG8_STAGE(PG8_SA(0, 0), a2, voffA);
.LBB0_781:
	s_add_u32 s44, s42, 0xfffc0080
	s_addc_u32 s45, s43, -1
	s_add_i32 s58, 0, 0x10000
	s_cmp_eq_u32 s57, 12
	s_cselect_b32 s47, s17, s45
	s_cselect_b32 s46, s39, s44
	v_add_u32_e32 v0, s58, v190
	s_cselect_b32 s45, s15, s56
	s_cselect_b32 s44, s54, s55
	s_add_i32 s60, 0, 0x14000
	ds_read_b128 v[130:133], v0
	ds_read_b128 v[134:137], v0 offset:1024
	ds_read_b128 v[138:141], v0 offset:2048
	ds_read_b128 v[142:145], v0 offset:3072
	v_add_u32_e32 v0, s60, v190
	ds_read_b128 v[146:149], v0
	ds_read_b128 v[150:153], v0 offset:1024
	ds_read_b128 v[154:157], v0 offset:2048
	ds_read_b128 v[158:161], v0 offset:3072
	v_lshl_add_u64 v[170:171], s[42:43], 0, v[176:177]
	s_add_i32 m0, s37, 0xc000
	ds_read_b128 v[180:183], v192
	ds_read_b128 v[184:187], v192 offset:1024
	ds_read_b128 v[216:219], v192 offset:2048
	ds_read_b128 v[220:223], v192 offset:3072
	ds_read_b128 v[224:227], v192 offset:4096
	ds_read_b128 v[228:231], v192 offset:5120
	ds_read_b128 v[232:235], v192 offset:6144
	ds_read_b128 v[236:239], v192 offset:7168
	global_load_lds_dwordx4 v[170:171], off
	v_lshl_add_u64 v[170:171], s[42:43], 0, v[178:179]
	s_add_i32 m0, s37, 0xe000
	s_nop 0
	global_load_lds_dwordx4 v[170:171], off
	s_waitcnt vmcnt(8)
	s_waitcnt lgkmcnt(0)
	s_barrier
	s_waitcnt lgkmcnt(0)
	v_mfma_f32_16x16x32_bf16 v[126:129], v[130:133], v[180:183], v[126:129]
	v_mfma_f32_16x16x32_bf16 v[122:125], v[138:141], v[180:183], v[122:125]
	v_mfma_f32_16x16x32_bf16 v[110:113], v[130:133], v[216:219], v[110:113]
	v_mfma_f32_16x16x32_bf16 v[106:109], v[138:141], v[216:219], v[106:109]
	v_mfma_f32_16x16x32_bf16 v[94:97], v[130:133], v[224:227], v[94:97]
	v_mfma_f32_16x16x32_bf16 v[90:93], v[138:141], v[224:227], v[90:93]
	v_mfma_f32_16x16x32_bf16 v[82:85], v[130:133], v[232:235], v[82:85]
	v_mfma_f32_16x16x32_bf16 v[78:81], v[138:141], v[232:235], v[78:81]
	v_mfma_f32_16x16x32_bf16 v[126:129], v[134:137], v[184:187], v[126:129]
	v_mfma_f32_16x16x32_bf16 v[122:125], v[142:145], v[184:187], v[122:125]
	v_mfma_f32_16x16x32_bf16 v[110:113], v[134:137], v[220:223], v[110:113]
	v_mfma_f32_16x16x32_bf16 v[106:109], v[142:145], v[220:223], v[106:109]
	v_mfma_f32_16x16x32_bf16 v[94:97], v[134:137], v[228:231], v[94:97]
	v_mfma_f32_16x16x32_bf16 v[90:93], v[142:145], v[228:231], v[90:93]
	v_mfma_f32_16x16x32_bf16 v[82:85], v[134:137], v[236:239], v[82:85]
	v_mfma_f32_16x16x32_bf16 v[78:81], v[142:145], v[236:239], v[78:81]
	v_mfma_f32_16x16x32_bf16 v[118:121], v[146:149], v[180:183], v[118:121]
	v_mfma_f32_16x16x32_bf16 v[114:117], v[154:157], v[180:183], v[114:117]
	v_mfma_f32_16x16x32_bf16 v[102:105], v[146:149], v[216:219], v[102:105]
	v_mfma_f32_16x16x32_bf16 v[98:101], v[154:157], v[216:219], v[98:101]
	v_mfma_f32_16x16x32_bf16 v[86:89], v[146:149], v[224:227], v[86:89]
	v_mfma_f32_16x16x32_bf16 v[74:77], v[154:157], v[224:227], v[74:77]
	v_mfma_f32_16x16x32_bf16 v[70:73], v[146:149], v[232:235], v[70:73]
	v_mfma_f32_16x16x32_bf16 v[66:69], v[154:157], v[232:235], v[66:69]
	v_mfma_f32_16x16x32_bf16 v[118:121], v[150:153], v[184:187], v[118:121]
	v_mfma_f32_16x16x32_bf16 v[114:117], v[158:161], v[184:187], v[114:117]
	v_mfma_f32_16x16x32_bf16 v[102:105], v[150:153], v[220:223], v[102:105]
	v_mfma_f32_16x16x32_bf16 v[98:101], v[158:161], v[220:223], v[98:101]
	v_mfma_f32_16x16x32_bf16 v[86:89], v[150:153], v[228:231], v[86:89]
	v_mfma_f32_16x16x32_bf16 v[74:77], v[158:161], v[228:231], v[74:77]
	v_mfma_f32_16x16x32_bf16 v[70:73], v[150:153], v[236:239], v[70:73]
	v_mfma_f32_16x16x32_bf16 v[66:69], v[158:161], v[236:239], v[66:69]
	s_barrier
	s_add_i32 s58, s58, s2
	v_lshl_add_u64 v[170:171], s[44:45], 0, v[164:165]
	s_mov_b32 m0, s58
	ds_read_b128 v[180:183], v192 offset:16384
	ds_read_b128 v[184:187], v192 offset:17408
	ds_read_b128 v[216:219], v192 offset:18432
	ds_read_b128 v[220:223], v192 offset:19456
	ds_read_b128 v[224:227], v192 offset:20480
	ds_read_b128 v[228:231], v192 offset:21504
	ds_read_b128 v[232:235], v192 offset:22528
	ds_read_b128 v[236:239], v192 offset:23552
	global_load_lds_dwordx4 v[170:171], off
	s_add_i32 m0, s58, 0x2000
	s_add_u32 s58, s44, 0x40000
	v_lshl_add_u64 v[172:173], s[44:45], 0, v[162:163]
	s_addc_u32 s59, s45, 0
	s_add_i32 s60, s60, s2
	global_load_lds_dwordx4 v[172:173], off
	v_lshl_add_u64 v[188:189], s[58:59], 0, v[164:165]
	s_mov_b32 m0, s60
	v_lshl_add_u64 v[194:195], s[46:47], 0, v[162:163]
	global_load_lds_dwordx4 v[188:189], off
	v_lshl_add_u64 v[188:189], s[58:59], 0, v[162:163]
	s_add_i32 m0, s60, 0x2000
	s_nop 0
	global_load_lds_dwordx4 v[188:189], off
	v_lshl_add_u64 v[188:189], s[46:47], 0, v[164:165]
	s_mov_b32 m0, s37
	s_nop 0
	global_load_lds_dwordx4 v[188:189], off
	s_mov_b32 m0, s41
	s_nop 0
	global_load_lds_dwordx4 v[194:195], off
	s_waitcnt vmcnt(8)
	s_waitcnt lgkmcnt(0)
	s_barrier
; #define PG8_STAGE(bufoff, gbase, voff) do { _Pragma("unroll") for (int _i = 0; _i < 2; ++_i) \
;         __builtin_amdgcn_global_load_lds((const unsigned*)((const char*)(gbase) + (voff)[_i]), (LAS unsigned*)(lds + (bufoff) + ldsw + _i * 8192), 16, 0, 0); } while (0)
; #define PG8_LDA(dst, b, h) do { _Pragma("unroll") for (int m = 0; m < 4; ++m) _Pragma("unroll") for (int k = 0; k < 2; ++k) dst[m][k] = *(const LAS bf16x8*)(lds + PG8_SA(b, h) + aoff + m * 2048 + k * 1024); } while (0)
; #define PG8_LDB(dst, b, h) do { _Pragma("unroll") for (int n = 0; n < 2; ++n) _Pragma("unroll") for (int k = 0; k < 2; ++k) dst[n][k] = *(const LAS bf16x8*)(lds + PG8_SB(b, h) + boff + n * 2048 + k * 1024); } while (0)
; #define PG8_MMA(ai, bj, At, Bt) do { __builtin_amdgcn_s_setprio(1); _Pragma("unroll") for (int m = 0; m < 4; ++m) _Pragma("unroll") for (int n = 0; n < 2; ++n) _Pragma("unroll") for (int k = 0; k < 2; ++k) \
;         acc[ai][bj][m][n] = __builtin_amdgcn_mfma_f32_16x16x32_bf16(Bt[n][k], At[m][k], acc[ai][bj][m][n], 0, 0, 0); __builtin_amdgcn_s_setprio(0); } while (0)
; #define PG8_WAIT_V(n) asm volatile("s_waitcnt vmcnt(" #n ")" ::: "memory")
; #define PG8_WAIT_L(n) asm volatile("s_waitcnt lgkmcnt(" #n ")" ::: "memory")
; #define PG8_BAR __builtin_amdgcn_s_barrier()
; #define PG8_SCHED __builtin_amdgcn_sched_barrier(0)
; template <class Epi, bool GS = false>
; __device__ __forceinline__ void gemm_phase(LAS unsigned char* lds, const Gemm g, const StaticOrder& S, const Epi& E, const int tid) {
;     ...
;             PG8_WAIT_V(8); PG8_WAIT_L(0); PG8_BAR; PG8_MMA(1, 0, At, B0); PG8_MMA(1, 1, At, B1); PG8_BAR; PG8_SCHED;
;             PG8_LDB(B0, 1, 0); PG8_LDB(B1, 1, 1); PG8_SCHED; PG8_LDA(At, 1, 0); PG8_STAGE(PG8_SA(0, 1), a2 + hstepA, voffA);
;             PG8_WAIT_V(8); PG8_WAIT_L(0); PG8_BAR; PG8_MMA(0, 0, At, B0); PG8_MMA(0, 1, At, B1); PG8_BAR; PG8_SCHED;
;             PG8_LDA(At, 1, 1); PG8_STAGE(PG8_SB(1, 0), b3, voffB); PG8_STAGE(PG8_SB(1, 1), b3 + hstepB, voffB); PG8_STAGE(PG8_SA(1, 0), a3, voffA);
;             PG8_WAIT_V(8); PG8_WAIT_L(0); PG8_BAR; PG8_MMA(1, 0, At, B0); PG8_MMA(1, 1, At, B1); PG8_BAR; PG8_SCHED;
	s_waitcnt lgkmcnt(0)
	v_mfma_f32_16x16x32_bf16 v[62:65], v[130:133], v[180:183], v[62:65]
	v_mfma_f32_16x16x32_bf16 v[58:61], v[138:141], v[180:183], v[58:61]
	v_mfma_f32_16x16x32_bf16 v[46:49], v[130:133], v[216:219], v[46:49]
	v_mfma_f32_16x16x32_bf16 v[42:45], v[138:141], v[216:219], v[42:45]
	v_mfma_f32_16x16x32_bf16 v[30:33], v[130:133], v[224:227], v[30:33]
	v_mfma_f32_16x16x32_bf16 v[26:29], v[138:141], v[224:227], v[26:29]
	v_mfma_f32_16x16x32_bf16 v[14:17], v[130:133], v[232:235], v[14:17]
	v_mfma_f32_16x16x32_bf16 v[10:13], v[138:141], v[232:235], v[10:13]
	v_mfma_f32_16x16x32_bf16 v[62:65], v[134:137], v[184:187], v[62:65]
	v_mfma_f32_16x16x32_bf16 v[58:61], v[142:145], v[184:187], v[58:61]
	v_mfma_f32_16x16x32_bf16 v[46:49], v[134:137], v[220:223], v[46:49]
	v_mfma_f32_16x16x32_bf16 v[42:45], v[142:145], v[220:223], v[42:45]
	v_mfma_f32_16x16x32_bf16 v[30:33], v[134:137], v[228:231], v[30:33]
	v_mfma_f32_16x16x32_bf16 v[26:29], v[142:145], v[228:231], v[26:29]
	v_mfma_f32_16x16x32_bf16 v[14:17], v[134:137], v[236:239], v[14:17]
	v_mfma_f32_16x16x32_bf16 v[10:13], v[142:145], v[236:239], v[10:13]
	v_mfma_f32_16x16x32_bf16 v[54:57], v[146:149], v[180:183], v[54:57]
	v_mfma_f32_16x16x32_bf16 v[50:53], v[154:157], v[180:183], v[50:53]
	v_mfma_f32_16x16x32_bf16 v[38:41], v[146:149], v[216:219], v[38:41]
	v_mfma_f32_16x16x32_bf16 v[34:37], v[154:157], v[216:219], v[34:37]
	v_mfma_f32_16x16x32_bf16 v[22:25], v[146:149], v[224:227], v[22:25]
	v_mfma_f32_16x16x32_bf16 v[18:21], v[154:157], v[224:227], v[18:21]
	v_mfma_f32_16x16x32_bf16 v[6:9], v[146:149], v[232:235], v[6:9]
	v_mfma_f32_16x16x32_bf16 v[2:5], v[154:157], v[232:235], v[2:5]
	v_mfma_f32_16x16x32_bf16 v[54:57], v[150:153], v[184:187], v[54:57]
	v_mfma_f32_16x16x32_bf16 v[50:53], v[158:161], v[184:187], v[50:53]
	v_mfma_f32_16x16x32_bf16 v[38:41], v[150:153], v[220:223], v[38:41]
	v_mfma_f32_16x16x32_bf16 v[34:37], v[158:161], v[220:223], v[34:37]
	v_mfma_f32_16x16x32_bf16 v[22:25], v[150:153], v[228:231], v[22:25]
	v_mfma_f32_16x16x32_bf16 v[18:21], v[158:161], v[228:231], v[18:21]
	v_mfma_f32_16x16x32_bf16 v[6:9], v[150:153], v[236:239], v[6:9]
	v_mfma_f32_16x16x32_bf16 v[2:5], v[158:161], v[236:239], v[2:5]
	s_barrier
	s_add_i32 s58, 0, 0x18000
	v_add_u32_e32 v0, s58, v190
	s_add_i32 s59, 0, 0x1c000
	ds_read_b128 v[130:133], v0
	ds_read_b128 v[134:137], v0 offset:1024
	ds_read_b128 v[138:141], v0 offset:2048
	ds_read_b128 v[142:145], v0 offset:3072
	v_add_u32_e32 v0, s59, v190
	ds_read_b128 v[146:149], v0
	ds_read_b128 v[150:153], v0 offset:1024
	ds_read_b128 v[154:157], v0 offset:2048
	ds_read_b128 v[158:161], v0 offset:3072
	s_add_u32 s46, s46, 0x40000
	s_addc_u32 s47, s47, 0
	s_mov_b32 m0, s48
	v_lshl_add_u64 v[240:241], s[46:47], 0, v[164:165]
	ds_read_b128 v[180:183], v192 offset:32768
	ds_read_b128 v[184:187], v192 offset:33792
	ds_read_b128 v[216:219], v192 offset:34816
	ds_read_b128 v[220:223], v192 offset:35840
	ds_read_b128 v[224:227], v192 offset:36864
	ds_read_b128 v[228:231], v192 offset:37888
	ds_read_b128 v[232:235], v192 offset:38912
	ds_read_b128 v[236:239], v192 offset:39936
	global_load_lds_dwordx4 v[240:241], off
	v_lshl_add_u64 v[240:241], s[46:47], 0, v[162:163]
	s_mov_b32 m0, s49
	s_nop 0
	global_load_lds_dwordx4 v[240:241], off
	s_waitcnt vmcnt(8)
	s_waitcnt lgkmcnt(0)
	s_barrier
	s_waitcnt lgkmcnt(0)
	v_mfma_f32_16x16x32_bf16 v[126:129], v[130:133], v[180:183], v[126:129]
	v_mfma_f32_16x16x32_bf16 v[122:125], v[138:141], v[180:183], v[122:125]
	v_mfma_f32_16x16x32_bf16 v[110:113], v[130:133], v[216:219], v[110:113]
	v_mfma_f32_16x16x32_bf16 v[106:109], v[138:141], v[216:219], v[106:109]
	v_mfma_f32_16x16x32_bf16 v[94:97], v[130:133], v[224:227], v[94:97]
	v_mfma_f32_16x16x32_bf16 v[90:93], v[138:141], v[224:227], v[90:93]
	v_mfma_f32_16x16x32_bf16 v[82:85], v[130:133], v[232:235], v[82:85]
	v_mfma_f32_16x16x32_bf16 v[78:81], v[138:141], v[232:235], v[78:81]
	v_mfma_f32_16x16x32_bf16 v[126:129], v[134:137], v[184:187], v[126:129]
	v_mfma_f32_16x16x32_bf16 v[122:125], v[142:145], v[184:187], v[122:125]
	v_mfma_f32_16x16x32_bf16 v[110:113], v[134:137], v[220:223], v[110:113]
	v_mfma_f32_16x16x32_bf16 v[106:109], v[142:145], v[220:223], v[106:109]
	v_mfma_f32_16x16x32_bf16 v[94:97], v[134:137], v[228:231], v[94:97]
	v_mfma_f32_16x16x32_bf16 v[90:93], v[142:145], v[228:231], v[90:93]
	v_mfma_f32_16x16x32_bf16 v[82:85], v[134:137], v[236:239], v[82:85]
	v_mfma_f32_16x16x32_bf16 v[78:81], v[142:145], v[236:239], v[78:81]
	v_mfma_f32_16x16x32_bf16 v[118:121], v[146:149], v[180:183], v[118:121]
	v_mfma_f32_16x16x32_bf16 v[114:117], v[154:157], v[180:183], v[114:117]
	v_mfma_f32_16x16x32_bf16 v[102:105], v[146:149], v[216:219], v[102:105]
	v_mfma_f32_16x16x32_bf16 v[98:101], v[154:157], v[216:219], v[98:101]
	v_mfma_f32_16x16x32_bf16 v[86:89], v[146:149], v[224:227], v[86:89]
	v_mfma_f32_16x16x32_bf16 v[74:77], v[154:157], v[224:227], v[74:77]
	v_mfma_f32_16x16x32_bf16 v[70:73], v[146:149], v[232:235], v[70:73]
	v_mfma_f32_16x16x32_bf16 v[66:69], v[154:157], v[232:235], v[66:69]
	v_mfma_f32_16x16x32_bf16 v[118:121], v[150:153], v[184:187], v[118:121]
	v_mfma_f32_16x16x32_bf16 v[114:117], v[158:161], v[184:187], v[114:117]
	v_mfma_f32_16x16x32_bf16 v[102:105], v[150:153], v[220:223], v[102:105]
	v_mfma_f32_16x16x32_bf16 v[98:101], v[158:161], v[220:223], v[98:101]
	v_mfma_f32_16x16x32_bf16 v[86:89], v[150:153], v[228:231], v[86:89]
	v_mfma_f32_16x16x32_bf16 v[74:77], v[158:161], v[228:231], v[74:77]
	v_mfma_f32_16x16x32_bf16 v[70:73], v[150:153], v[236:239], v[70:73]
	v_mfma_f32_16x16x32_bf16 v[66:69], v[158:161], v[236:239], v[66:69]
	s_barrier
; #define PG8_STAGE(bufoff, gbase, voff) do { _Pragma("unroll") for (int _i = 0; _i < 2; ++_i) \
;         __builtin_amdgcn_global_load_lds((const unsigned*)((const char*)(gbase) + (voff)[_i]), (LAS unsigned*)(lds + (bufoff) + ldsw + _i * 8192), 16, 0, 0); } while (0)
; #define PG8_LDA(dst, b, h) do { _Pragma("unroll") for (int m = 0; m < 4; ++m) _Pragma("unroll") for (int k = 0; k < 2; ++k) dst[m][k] = *(const LAS bf16x8*)(lds + PG8_SA(b, h) + aoff + m * 2048 + k * 1024); } while (0)
; #define PG8_LDB(dst, b, h) do { _Pragma("unroll") for (int n = 0; n < 2; ++n) _Pragma("unroll") for (int k = 0; k < 2; ++k) dst[n][k] = *(const LAS bf16x8*)(lds + PG8_SB(b, h) + boff + n * 2048 + k * 1024); } while (0)
; #define PG8_MMA(ai, bj, At, Bt) do { __builtin_amdgcn_s_setprio(1); _Pragma("unroll") for (int m = 0; m < 4; ++m) _Pragma("unroll") for (int n = 0; n < 2; ++n) _Pragma("unroll") for (int k = 0; k < 2; ++k) \
;         acc[ai][bj][m][n] = __builtin_amdgcn_mfma_f32_16x16x32_bf16(Bt[n][k], At[m][k], acc[ai][bj][m][n], 0, 0, 0); __builtin_amdgcn_s_setprio(0); } while (0)
; #define PG8_WAIT_V(n) asm volatile("s_waitcnt vmcnt(" #n ")" ::: "memory")
; #define PG8_WAIT_L(n) asm volatile("s_waitcnt lgkmcnt(" #n ")" ::: "memory")
; #define PG8_BAR __builtin_amdgcn_s_barrier()
; #define PG8_SCHED __builtin_amdgcn_sched_barrier(0)
; template <class Epi, bool GS = false>
; __device__ __forceinline__ void gemm_phase(LAS unsigned char* lds, const Gemm g, const StaticOrder& S, const Epi& E, const int tid) {
;     ...
;             PG8_LDB(B0, 1, 0); PG8_LDB(B1, 1, 1); PG8_SCHED; PG8_LDA(At, 1, 0); PG8_STAGE(PG8_SA(0, 1), a2 + hstepA, voffA);
;             PG8_WAIT_V(8); PG8_WAIT_L(0); PG8_BAR; PG8_MMA(0, 0, At, B0); PG8_MMA(0, 1, At, B1); PG8_BAR; PG8_SCHED;
;             PG8_LDA(At, 1, 1); PG8_STAGE(PG8_SB(1, 0), b3, voffB); PG8_STAGE(PG8_SB(1, 1), b3 + hstepB, voffB); PG8_STAGE(PG8_SA(1, 0), a3, voffA);
;             PG8_WAIT_V(8); PG8_WAIT_L(0); PG8_BAR; PG8_MMA(1, 0, At, B0); PG8_MMA(1, 1, At, B1); PG8_BAR; PG8_SCHED;
;         }
;     ...
;         if (wr == 0) PG8_BAR;
	s_add_i32 s46, s58, s2
	v_lshl_add_u64 v[170:171], v[170:171], 0, s[0:1]
	s_mov_b32 m0, s46
	ds_read_b128 v[180:183], v192 offset:49152
	ds_read_b128 v[184:187], v192 offset:50176
	ds_read_b128 v[216:219], v192 offset:51200
	ds_read_b128 v[220:223], v192 offset:52224
	ds_read_b128 v[224:227], v192 offset:53248
	ds_read_b128 v[228:231], v192 offset:54272
	ds_read_b128 v[232:235], v192 offset:55296
	ds_read_b128 v[236:239], v192 offset:56320
	global_load_lds_dwordx4 v[170:171], off
	s_add_i32 m0, s46, 0x2000
	s_add_u32 s44, s44, 0x40080
	v_lshl_add_u64 v[170:171], v[172:173], 0, s[0:1]
	s_addc_u32 s45, s45, 0
	s_add_i32 s46, s59, s2
	global_load_lds_dwordx4 v[170:171], off
	v_lshl_add_u64 v[170:171], s[44:45], 0, v[164:165]
	s_mov_b32 m0, s46
	s_nop 0
	global_load_lds_dwordx4 v[170:171], off
	v_lshl_add_u64 v[170:171], s[44:45], 0, v[162:163]
	s_add_i32 m0, s46, 0x2000
	s_nop 0
	global_load_lds_dwordx4 v[170:171], off
	v_lshl_add_u64 v[170:171], v[188:189], 0, s[0:1]
	s_mov_b32 m0, s50
	s_nop 0
	global_load_lds_dwordx4 v[170:171], off
	v_lshl_add_u64 v[170:171], v[194:195], 0, s[0:1]
	s_mov_b32 m0, s51
	s_nop 0
	global_load_lds_dwordx4 v[170:171], off
	s_waitcnt vmcnt(8)
	s_waitcnt lgkmcnt(0)
	s_barrier
	s_waitcnt lgkmcnt(0)
	v_mfma_f32_16x16x32_bf16 v[62:65], v[130:133], v[180:183], v[62:65]
	v_mfma_f32_16x16x32_bf16 v[58:61], v[138:141], v[180:183], v[58:61]
	v_mfma_f32_16x16x32_bf16 v[46:49], v[130:133], v[216:219], v[46:49]
	v_mfma_f32_16x16x32_bf16 v[42:45], v[138:141], v[216:219], v[42:45]
	v_mfma_f32_16x16x32_bf16 v[30:33], v[130:133], v[224:227], v[30:33]
	v_mfma_f32_16x16x32_bf16 v[26:29], v[138:141], v[224:227], v[26:29]
	v_mfma_f32_16x16x32_bf16 v[14:17], v[130:133], v[232:235], v[14:17]
	v_mfma_f32_16x16x32_bf16 v[10:13], v[138:141], v[232:235], v[10:13]
	v_mfma_f32_16x16x32_bf16 v[62:65], v[134:137], v[184:187], v[62:65]
	v_mfma_f32_16x16x32_bf16 v[58:61], v[142:145], v[184:187], v[58:61]
	v_mfma_f32_16x16x32_bf16 v[46:49], v[134:137], v[220:223], v[46:49]
	v_mfma_f32_16x16x32_bf16 v[42:45], v[142:145], v[220:223], v[42:45]
	v_mfma_f32_16x16x32_bf16 v[30:33], v[134:137], v[228:231], v[30:33]
	v_mfma_f32_16x16x32_bf16 v[26:29], v[142:145], v[228:231], v[26:29]
	v_mfma_f32_16x16x32_bf16 v[14:17], v[134:137], v[236:239], v[14:17]
	v_mfma_f32_16x16x32_bf16 v[10:13], v[142:145], v[236:239], v[10:13]
	v_mfma_f32_16x16x32_bf16 v[54:57], v[146:149], v[180:183], v[54:57]
	v_mfma_f32_16x16x32_bf16 v[50:53], v[154:157], v[180:183], v[50:53]
	v_mfma_f32_16x16x32_bf16 v[38:41], v[146:149], v[216:219], v[38:41]
	v_mfma_f32_16x16x32_bf16 v[34:37], v[154:157], v[216:219], v[34:37]
	v_mfma_f32_16x16x32_bf16 v[22:25], v[146:149], v[224:227], v[22:25]
	v_mfma_f32_16x16x32_bf16 v[18:21], v[154:157], v[224:227], v[18:21]
	v_mfma_f32_16x16x32_bf16 v[6:9], v[146:149], v[232:235], v[6:9]
	v_mfma_f32_16x16x32_bf16 v[2:5], v[154:157], v[232:235], v[2:5]
	v_mfma_f32_16x16x32_bf16 v[54:57], v[150:153], v[184:187], v[54:57]
	v_mfma_f32_16x16x32_bf16 v[50:53], v[158:161], v[184:187], v[50:53]
	v_mfma_f32_16x16x32_bf16 v[38:41], v[150:153], v[220:223], v[38:41]
	v_mfma_f32_16x16x32_bf16 v[34:37], v[158:161], v[220:223], v[34:37]
	v_mfma_f32_16x16x32_bf16 v[22:25], v[150:153], v[228:231], v[22:25]
	v_mfma_f32_16x16x32_bf16 v[18:21], v[158:161], v[228:231], v[18:21]
	v_mfma_f32_16x16x32_bf16 v[6:9], v[150:153], v[236:239], v[6:9]
	v_mfma_f32_16x16x32_bf16 v[2:5], v[158:161], v[236:239], v[2:5]
	s_barrier
	s_add_i32 s57, s57, 2
	s_add_u32 s42, s42, 0x100
	s_addc_u32 s43, s43, 0
	s_add_u32 s55, s55, 0x100
	s_addc_u32 s56, s56, 0
	s_cmp_gt_u32 s57, 13
	s_cbranch_scc0 .LBB0_781
	s_and_b64 vcc, exec, s[8:9]
	s_cbranch_vccz .LBB0_784
	s_barrier

; #define PG8_STAGE(bufoff, gbase, voff) do { _Pragma("unroll") for (int _i = 0; _i < 2; ++_i) \
;         __builtin_amdgcn_global_load_lds((const unsigned*)((const char*)(gbase) + (voff)[_i]), (LAS unsigned*)(lds + (bufoff) + ldsw + _i * 8192), 16, 0, 0); } while (0)
; #define PG8_LDA(dst, b, h) do { _Pragma("unroll") for (int m = 0; m < 4; ++m) _Pragma("unroll") for (int k = 0; k < 2; ++k) dst[m][k] = *(const LAS bf16x8*)(lds + PG8_SA(b, h) + aoff + m * 2048 + k * 1024); } while (0)
; #define PG8_LDB(dst, b, h) do { _Pragma("unroll") for (int n = 0; n < 2; ++n) _Pragma("unroll") for (int k = 0; k < 2; ++k) dst[n][k] = *(const LAS bf16x8*)(lds + PG8_SB(b, h) + boff + n * 2048 + k * 1024); } while (0)
; #define PG8_MMA(ai, bj, At, Bt) do { __builtin_amdgcn_s_setprio(1); _Pragma("unroll") for (int m = 0; m < 4; ++m) _Pragma("unroll") for (int n = 0; n < 2; ++n) _Pragma("unroll") for (int k = 0; k < 2; ++k) \
;         acc[ai][bj][m][n] = __builtin_amdgcn_mfma_f32_16x16x32_bf16(Bt[n][k], At[m][k], acc[ai][bj][m][n], 0, 0, 0); __builtin_amdgcn_s_setprio(0); } while (0)
; #define PG8_WAIT_V(n) asm volatile("s_waitcnt vmcnt(" #n ")" ::: "memory")
; #define PG8_WAIT_L(n) asm volatile("s_waitcnt lgkmcnt(" #n ")" ::: "memory")
; #define PG8_BAR __builtin_amdgcn_s_barrier()
; #define PG8_SCHED __builtin_amdgcn_sched_barrier(0)
; template <class Epi, bool GS = false>
; __device__ __forceinline__ void gemm_phase(LAS unsigned char* lds, const Gemm g, const StaticOrder& S, const Epi& E, const int tid) {
;     ...
;         for (int t = tg; t < tg + seg; t += 2) {
;             const bool last = (t == nt - 2);
;             const char* a1 = cA + (size_t)(t + 1) * kstep;
;             const char* a2 = last ? nA : cA + (size_t)(t + 2) * kstep; const char* b2 = last ? nB : cB + (size_t)(t + 2) * kstep;
;             const char* a3 = a2 + kstep; const char* b3 = b2 + kstep;
;             PG8_LDB(B0, 0, 0); PG8_LDB(B1, 0, 1); PG8_SCHED; PG8_LDA(At, 0, 0); PG8_STAGE(PG8_SA(1, 1), a1 + hstepA, voffA);
;             PG8_WAIT_V(8); PG8_WAIT_L(0); PG8_BAR; PG8_MMA(0, 0, At, B0); PG8_MMA(0, 1, At, B1); PG8_BAR; PG8_SCHED;
;             PG8_LDA(At, 0, 1); PG8_STAGE(PG8_SB(0, 0), b2, voffB); PG8_STAGE(PG8_SB(0, 1), b2 + hstepB, voffB); PG8_STAGE(PG8_SA(0, 0), a2, voffA);
.LBB0_921:
	s_add_u32 s30, s22, 0xfffc0080
	s_addc_u32 s31, s23, -1
	s_add_i32 s52, 0, 0x10000
	s_cmp_eq_u32 s51, 12
	s_cselect_b32 s35, s15, s31
	s_cselect_b32 s34, s47, s30
	v_add_u32_e32 v140, s52, v143
	s_cselect_b32 s31, s9, s50
	s_cselect_b32 s30, s48, s49
	s_add_i32 s54, 0, 0x14000
	ds_read_b128 v[146:149], v140
	ds_read_b128 v[150:153], v140 offset:1024
	ds_read_b128 v[154:157], v140 offset:2048
	ds_read_b128 v[158:161], v140 offset:3072
	v_add_u32_e32 v140, s54, v143
	ds_read_b128 v[162:165], v140
	ds_read_b128 v[176:179], v140 offset:1024
	ds_read_b128 v[180:183], v140 offset:2048
	ds_read_b128 v[184:187], v140 offset:3072
	v_lshl_add_u64 v[140:141], s[22:23], 0, v[136:137]
	s_add_i32 m0, s36, 0xc000
	ds_read_b128 v[188:191], v145
	ds_read_b128 v[192:195], v145 offset:1024
	ds_read_b128 v[216:219], v145 offset:2048
	ds_read_b128 v[220:223], v145 offset:3072
	ds_read_b128 v[224:227], v145 offset:4096
	ds_read_b128 v[228:231], v145 offset:5120
	ds_read_b128 v[232:235], v145 offset:6144
	ds_read_b128 v[236:239], v145 offset:7168
	global_load_lds_dwordx4 v[140:141], off
	v_lshl_add_u64 v[140:141], s[22:23], 0, v[138:139]
	s_add_i32 m0, s36, 0xe000
	s_nop 0
	global_load_lds_dwordx4 v[140:141], off
	s_waitcnt vmcnt(8)
	s_waitcnt lgkmcnt(0)
	s_barrier
	s_waitcnt lgkmcnt(0)
	v_mfma_f32_16x16x32_bf16 v[126:129], v[146:149], v[188:191], v[126:129]
	v_mfma_f32_16x16x32_bf16 v[118:121], v[154:157], v[188:191], v[118:121]
	v_mfma_f32_16x16x32_bf16 v[110:113], v[146:149], v[216:219], v[110:113]
	v_mfma_f32_16x16x32_bf16 v[102:105], v[154:157], v[216:219], v[102:105]
	v_mfma_f32_16x16x32_bf16 v[94:97], v[146:149], v[224:227], v[94:97]
	v_mfma_f32_16x16x32_bf16 v[86:89], v[154:157], v[224:227], v[86:89]
	v_mfma_f32_16x16x32_bf16 v[78:81], v[146:149], v[232:235], v[78:81]
	v_mfma_f32_16x16x32_bf16 v[70:73], v[154:157], v[232:235], v[70:73]
	v_mfma_f32_16x16x32_bf16 v[126:129], v[150:153], v[192:195], v[126:129]
	v_mfma_f32_16x16x32_bf16 v[118:121], v[158:161], v[192:195], v[118:121]
	v_mfma_f32_16x16x32_bf16 v[110:113], v[150:153], v[220:223], v[110:113]
	v_mfma_f32_16x16x32_bf16 v[102:105], v[158:161], v[220:223], v[102:105]
	v_mfma_f32_16x16x32_bf16 v[94:97], v[150:153], v[228:231], v[94:97]
	v_mfma_f32_16x16x32_bf16 v[86:89], v[158:161], v[228:231], v[86:89]
	v_mfma_f32_16x16x32_bf16 v[78:81], v[150:153], v[236:239], v[78:81]
	v_mfma_f32_16x16x32_bf16 v[70:73], v[158:161], v[236:239], v[70:73]
	v_mfma_f32_16x16x32_bf16 v[122:125], v[162:165], v[188:191], v[122:125]
	v_mfma_f32_16x16x32_bf16 v[114:117], v[180:183], v[188:191], v[114:117]
	v_mfma_f32_16x16x32_bf16 v[106:109], v[162:165], v[216:219], v[106:109]
	v_mfma_f32_16x16x32_bf16 v[98:101], v[180:183], v[216:219], v[98:101]
	v_mfma_f32_16x16x32_bf16 v[90:93], v[162:165], v[224:227], v[90:93]
	v_mfma_f32_16x16x32_bf16 v[82:85], v[180:183], v[224:227], v[82:85]
	v_mfma_f32_16x16x32_bf16 v[74:77], v[162:165], v[232:235], v[74:77]
	v_mfma_f32_16x16x32_bf16 v[66:69], v[180:183], v[232:235], v[66:69]
	v_mfma_f32_16x16x32_bf16 v[122:125], v[176:179], v[192:195], v[122:125]
	v_mfma_f32_16x16x32_bf16 v[114:117], v[184:187], v[192:195], v[114:117]
	v_mfma_f32_16x16x32_bf16 v[106:109], v[176:179], v[220:223], v[106:109]
	v_mfma_f32_16x16x32_bf16 v[98:101], v[184:187], v[220:223], v[98:101]
	v_mfma_f32_16x16x32_bf16 v[90:93], v[176:179], v[228:231], v[90:93]
	v_mfma_f32_16x16x32_bf16 v[82:85], v[184:187], v[228:231], v[82:85]
	v_mfma_f32_16x16x32_bf16 v[74:77], v[176:179], v[236:239], v[74:77]
	v_mfma_f32_16x16x32_bf16 v[66:69], v[184:187], v[236:239], v[66:69]
	s_barrier
	s_add_i32 s52, s52, s10
	v_lshl_add_u64 v[140:141], s[30:31], 0, v[0:1]
	s_mov_b32 m0, s52
	ds_read_b128 v[188:191], v145 offset:16384
	ds_read_b128 v[192:195], v145 offset:17408
	ds_read_b128 v[216:219], v145 offset:18432
	ds_read_b128 v[220:223], v145 offset:19456
	ds_read_b128 v[224:227], v145 offset:20480
	ds_read_b128 v[228:231], v145 offset:21504
	ds_read_b128 v[232:235], v145 offset:22528
	ds_read_b128 v[236:239], v145 offset:23552
	global_load_lds_dwordx4 v[140:141], off
	s_add_i32 m0, s52, 0x2000
	s_add_u32 s52, s30, 0x40000
	v_lshl_add_u64 v[240:241], s[30:31], 0, v[130:131]
	s_addc_u32 s53, s31, 0
	s_add_i32 s54, s54, s10
	global_load_lds_dwordx4 v[240:241], off
	v_lshl_add_u64 v[242:243], s[52:53], 0, v[0:1]
	s_mov_b32 m0, s54
	v_lshl_add_u64 v[244:245], s[34:35], 0, v[132:133]
	global_load_lds_dwordx4 v[242:243], off
	v_lshl_add_u64 v[242:243], s[52:53], 0, v[130:131]
	s_add_i32 m0, s54, 0x2000
	s_nop 0
	global_load_lds_dwordx4 v[242:243], off
	v_lshl_add_u64 v[242:243], s[34:35], 0, v[134:135]
	s_mov_b32 m0, s36
	s_nop 0
	global_load_lds_dwordx4 v[242:243], off
	s_mov_b32 m0, s37
	s_nop 0
	global_load_lds_dwordx4 v[244:245], off
	s_waitcnt vmcnt(8)
	s_waitcnt lgkmcnt(0)
	s_barrier
; #define PG8_STAGE(bufoff, gbase, voff) do { _Pragma("unroll") for (int _i = 0; _i < 2; ++_i) \
;         __builtin_amdgcn_global_load_lds((const unsigned*)((const char*)(gbase) + (voff)[_i]), (LAS unsigned*)(lds + (bufoff) + ldsw + _i * 8192), 16, 0, 0); } while (0)
; #define PG8_LDA(dst, b, h) do { _Pragma("unroll") for (int m = 0; m < 4; ++m) _Pragma("unroll") for (int k = 0; k < 2; ++k) dst[m][k] = *(const LAS bf16x8*)(lds + PG8_SA(b, h) + aoff + m * 2048 + k * 1024); } while (0)
; #define PG8_LDB(dst, b, h) do { _Pragma("unroll") for (int n = 0; n < 2; ++n) _Pragma("unroll") for (int k = 0; k < 2; ++k) dst[n][k] = *(const LAS bf16x8*)(lds + PG8_SB(b, h) + boff + n * 2048 + k * 1024); } while (0)
; #define PG8_MMA(ai, bj, At, Bt) do { __builtin_amdgcn_s_setprio(1); _Pragma("unroll") for (int m = 0; m < 4; ++m) _Pragma("unroll") for (int n = 0; n < 2; ++n) _Pragma("unroll") for (int k = 0; k < 2; ++k) \
;         acc[ai][bj][m][n] = __builtin_amdgcn_mfma_f32_16x16x32_bf16(Bt[n][k], At[m][k], acc[ai][bj][m][n], 0, 0, 0); __builtin_amdgcn_s_setprio(0); } while (0)
; #define PG8_WAIT_V(n) asm volatile("s_waitcnt vmcnt(" #n ")" ::: "memory")
; #define PG8_WAIT_L(n) asm volatile("s_waitcnt lgkmcnt(" #n ")" ::: "memory")
; #define PG8_BAR __builtin_amdgcn_s_barrier()
; #define PG8_SCHED __builtin_amdgcn_sched_barrier(0)
; template <class Epi, bool GS = false>
; __device__ __forceinline__ void gemm_phase(LAS unsigned char* lds, const Gemm g, const StaticOrder& S, const Epi& E, const int tid) {
;     ...
;             PG8_WAIT_V(8); PG8_WAIT_L(0); PG8_BAR; PG8_MMA(1, 0, At, B0); PG8_MMA(1, 1, At, B1); PG8_BAR; PG8_SCHED;
;             PG8_LDB(B0, 1, 0); PG8_LDB(B1, 1, 1); PG8_SCHED; PG8_LDA(At, 1, 0); PG8_STAGE(PG8_SA(0, 1), a2 + hstepA, voffA);
;             PG8_WAIT_V(8); PG8_WAIT_L(0); PG8_BAR; PG8_MMA(0, 0, At, B0); PG8_MMA(0, 1, At, B1); PG8_BAR; PG8_SCHED;
;             PG8_LDA(At, 1, 1); PG8_STAGE(PG8_SB(1, 0), b3, voffB); PG8_STAGE(PG8_SB(1, 1), b3 + hstepB, voffB); PG8_STAGE(PG8_SA(1, 0), a3, voffA);
;             PG8_WAIT_V(8); PG8_WAIT_L(0); PG8_BAR; PG8_MMA(1, 0, At, B0); PG8_MMA(1, 1, At, B1); PG8_BAR; PG8_SCHED;
	s_waitcnt lgkmcnt(0)
	v_mfma_f32_16x16x32_bf16 v[62:65], v[146:149], v[188:191], v[62:65]
	v_mfma_f32_16x16x32_bf16 v[54:57], v[154:157], v[188:191], v[54:57]
	v_mfma_f32_16x16x32_bf16 v[46:49], v[146:149], v[216:219], v[46:49]
	v_mfma_f32_16x16x32_bf16 v[38:41], v[154:157], v[216:219], v[38:41]
	v_mfma_f32_16x16x32_bf16 v[30:33], v[146:149], v[224:227], v[30:33]
	v_mfma_f32_16x16x32_bf16 v[22:25], v[154:157], v[224:227], v[22:25]
	v_mfma_f32_16x16x32_bf16 v[14:17], v[146:149], v[232:235], v[14:17]
	v_mfma_f32_16x16x32_bf16 v[6:9], v[154:157], v[232:235], v[6:9]
	v_mfma_f32_16x16x32_bf16 v[62:65], v[150:153], v[192:195], v[62:65]
	v_mfma_f32_16x16x32_bf16 v[54:57], v[158:161], v[192:195], v[54:57]
	v_mfma_f32_16x16x32_bf16 v[46:49], v[150:153], v[220:223], v[46:49]
	v_mfma_f32_16x16x32_bf16 v[38:41], v[158:161], v[220:223], v[38:41]
	v_mfma_f32_16x16x32_bf16 v[30:33], v[150:153], v[228:231], v[30:33]
	v_mfma_f32_16x16x32_bf16 v[22:25], v[158:161], v[228:231], v[22:25]
	v_mfma_f32_16x16x32_bf16 v[14:17], v[150:153], v[236:239], v[14:17]
	v_mfma_f32_16x16x32_bf16 v[6:9], v[158:161], v[236:239], v[6:9]
	v_mfma_f32_16x16x32_bf16 v[58:61], v[162:165], v[188:191], v[58:61]
	v_mfma_f32_16x16x32_bf16 v[50:53], v[180:183], v[188:191], v[50:53]
	v_mfma_f32_16x16x32_bf16 v[42:45], v[162:165], v[216:219], v[42:45]
	v_mfma_f32_16x16x32_bf16 v[34:37], v[180:183], v[216:219], v[34:37]
	v_mfma_f32_16x16x32_bf16 v[26:29], v[162:165], v[224:227], v[26:29]
	v_mfma_f32_16x16x32_bf16 v[18:21], v[180:183], v[224:227], v[18:21]
	v_mfma_f32_16x16x32_bf16 v[10:13], v[162:165], v[232:235], v[10:13]
	v_mfma_f32_16x16x32_bf16 v[2:5], v[180:183], v[232:235], v[2:5]
	v_mfma_f32_16x16x32_bf16 v[58:61], v[176:179], v[192:195], v[58:61]
	v_mfma_f32_16x16x32_bf16 v[50:53], v[184:187], v[192:195], v[50:53]
	v_mfma_f32_16x16x32_bf16 v[42:45], v[176:179], v[220:223], v[42:45]
	v_mfma_f32_16x16x32_bf16 v[34:37], v[184:187], v[220:223], v[34:37]
	v_mfma_f32_16x16x32_bf16 v[26:29], v[176:179], v[228:231], v[26:29]
	v_mfma_f32_16x16x32_bf16 v[18:21], v[184:187], v[228:231], v[18:21]
	v_mfma_f32_16x16x32_bf16 v[10:13], v[176:179], v[236:239], v[10:13]
	v_mfma_f32_16x16x32_bf16 v[2:5], v[184:187], v[236:239], v[2:5]
	s_barrier
	s_add_i32 s52, 0, 0x18000
	s_add_i32 s53, 0, 0x1c000
	v_add_u32_e32 v158, s52, v143
	v_add_u32_e32 v169, s53, v143
	ds_read_b128 v[146:149], v158
	ds_read_b128 v[150:153], v158 offset:1024
	ds_read_b128 v[154:157], v158 offset:2048
	ds_read_b128 v[158:161], v158 offset:3072
	ds_read_b128 v[162:165], v169
	ds_read_b128 v[176:179], v169 offset:1024
	ds_read_b128 v[180:183], v169 offset:2048
	ds_read_b128 v[184:187], v169 offset:3072
	s_add_u32 s34, s34, 0x40000
	s_addc_u32 s35, s35, 0
	s_mov_b32 m0, s40
	v_lshl_add_u64 v[246:247], s[34:35], 0, v[134:135]
	ds_read_b128 v[188:191], v145 offset:32768
	ds_read_b128 v[192:195], v145 offset:33792
	ds_read_b128 v[216:219], v145 offset:34816
	ds_read_b128 v[220:223], v145 offset:35840
	ds_read_b128 v[224:227], v145 offset:36864
	ds_read_b128 v[228:231], v145 offset:37888
	ds_read_b128 v[232:235], v145 offset:38912
	ds_read_b128 v[236:239], v145 offset:39936
	global_load_lds_dwordx4 v[246:247], off
	v_lshl_add_u64 v[246:247], s[34:35], 0, v[132:133]
	s_mov_b32 m0, s41
	s_nop 0
	global_load_lds_dwordx4 v[246:247], off
	s_waitcnt vmcnt(8)
	s_waitcnt lgkmcnt(0)
	s_barrier
	s_waitcnt lgkmcnt(0)
	v_mfma_f32_16x16x32_bf16 v[126:129], v[146:149], v[188:191], v[126:129]
	v_mfma_f32_16x16x32_bf16 v[118:121], v[154:157], v[188:191], v[118:121]
	v_mfma_f32_16x16x32_bf16 v[110:113], v[146:149], v[216:219], v[110:113]
	v_mfma_f32_16x16x32_bf16 v[102:105], v[154:157], v[216:219], v[102:105]
	v_mfma_f32_16x16x32_bf16 v[94:97], v[146:149], v[224:227], v[94:97]
	v_mfma_f32_16x16x32_bf16 v[86:89], v[154:157], v[224:227], v[86:89]
	v_mfma_f32_16x16x32_bf16 v[78:81], v[146:149], v[232:235], v[78:81]
	v_mfma_f32_16x16x32_bf16 v[70:73], v[154:157], v[232:235], v[70:73]
	v_mfma_f32_16x16x32_bf16 v[126:129], v[150:153], v[192:195], v[126:129]
	v_mfma_f32_16x16x32_bf16 v[118:121], v[158:161], v[192:195], v[118:121]
	v_mfma_f32_16x16x32_bf16 v[110:113], v[150:153], v[220:223], v[110:113]
	v_mfma_f32_16x16x32_bf16 v[102:105], v[158:161], v[220:223], v[102:105]
	v_mfma_f32_16x16x32_bf16 v[94:97], v[150:153], v[228:231], v[94:97]
	v_mfma_f32_16x16x32_bf16 v[86:89], v[158:161], v[228:231], v[86:89]
	v_mfma_f32_16x16x32_bf16 v[78:81], v[150:153], v[236:239], v[78:81]
	v_mfma_f32_16x16x32_bf16 v[70:73], v[158:161], v[236:239], v[70:73]
	v_mfma_f32_16x16x32_bf16 v[122:125], v[162:165], v[188:191], v[122:125]
	v_mfma_f32_16x16x32_bf16 v[114:117], v[180:183], v[188:191], v[114:117]
	v_mfma_f32_16x16x32_bf16 v[106:109], v[162:165], v[216:219], v[106:109]
	v_mfma_f32_16x16x32_bf16 v[98:101], v[180:183], v[216:219], v[98:101]
	v_mfma_f32_16x16x32_bf16 v[90:93], v[162:165], v[224:227], v[90:93]
	v_mfma_f32_16x16x32_bf16 v[82:85], v[180:183], v[224:227], v[82:85]
	v_mfma_f32_16x16x32_bf16 v[74:77], v[162:165], v[232:235], v[74:77]
	v_mfma_f32_16x16x32_bf16 v[66:69], v[180:183], v[232:235], v[66:69]
	v_mfma_f32_16x16x32_bf16 v[122:125], v[176:179], v[192:195], v[122:125]
	v_mfma_f32_16x16x32_bf16 v[114:117], v[184:187], v[192:195], v[114:117]
	v_mfma_f32_16x16x32_bf16 v[106:109], v[176:179], v[220:223], v[106:109]
	v_mfma_f32_16x16x32_bf16 v[98:101], v[184:187], v[220:223], v[98:101]
	v_mfma_f32_16x16x32_bf16 v[90:93], v[176:179], v[228:231], v[90:93]
	v_mfma_f32_16x16x32_bf16 v[82:85], v[184:187], v[228:231], v[82:85]
	v_mfma_f32_16x16x32_bf16 v[74:77], v[176:179], v[236:239], v[74:77]
	v_mfma_f32_16x16x32_bf16 v[66:69], v[184:187], v[236:239], v[66:69]
	s_barrier
; #define PG8_STAGE(bufoff, gbase, voff) do { _Pragma("unroll") for (int _i = 0; _i < 2; ++_i) \
;         __builtin_amdgcn_global_load_lds((const unsigned*)((const char*)(gbase) + (voff)[_i]), (LAS unsigned*)(lds + (bufoff) + ldsw + _i * 8192), 16, 0, 0); } while (0)
; #define PG8_LDA(dst, b, h) do { _Pragma("unroll") for (int m = 0; m < 4; ++m) _Pragma("unroll") for (int k = 0; k < 2; ++k) dst[m][k] = *(const LAS bf16x8*)(lds + PG8_SA(b, h) + aoff + m * 2048 + k * 1024); } while (0)
; #define PG8_LDB(dst, b, h) do { _Pragma("unroll") for (int n = 0; n < 2; ++n) _Pragma("unroll") for (int k = 0; k < 2; ++k) dst[n][k] = *(const LAS bf16x8*)(lds + PG8_SB(b, h) + boff + n * 2048 + k * 1024); } while (0)
; #define PG8_MMA(ai, bj, At, Bt) do { __builtin_amdgcn_s_setprio(1); _Pragma("unroll") for (int m = 0; m < 4; ++m) _Pragma("unroll") for (int n = 0; n < 2; ++n) _Pragma("unroll") for (int k = 0; k < 2; ++k) \
;         acc[ai][bj][m][n] = __builtin_amdgcn_mfma_f32_16x16x32_bf16(Bt[n][k], At[m][k], acc[ai][bj][m][n], 0, 0, 0); __builtin_amdgcn_s_setprio(0); } while (0)
; #define PG8_WAIT_V(n) asm volatile("s_waitcnt vmcnt(" #n ")" ::: "memory")
; #define PG8_WAIT_L(n) asm volatile("s_waitcnt lgkmcnt(" #n ")" ::: "memory")
; #define PG8_BAR __builtin_amdgcn_s_barrier()
; #define PG8_SCHED __builtin_amdgcn_sched_barrier(0)
; template <class Epi, bool GS = false>
; __device__ __forceinline__ void gemm_phase(LAS unsigned char* lds, const Gemm g, const StaticOrder& S, const Epi& E, const int tid) {
;     ...
;             PG8_LDB(B0, 1, 0); PG8_LDB(B1, 1, 1); PG8_SCHED; PG8_LDA(At, 1, 0); PG8_STAGE(PG8_SA(0, 1), a2 + hstepA, voffA);
;             PG8_WAIT_V(8); PG8_WAIT_L(0); PG8_BAR; PG8_MMA(0, 0, At, B0); PG8_MMA(0, 1, At, B1); PG8_BAR; PG8_SCHED;
;             PG8_LDA(At, 1, 1); PG8_STAGE(PG8_SB(1, 0), b3, voffB); PG8_STAGE(PG8_SB(1, 1), b3 + hstepB, voffB); PG8_STAGE(PG8_SA(1, 0), a3, voffA);
;             PG8_WAIT_V(8); PG8_WAIT_L(0); PG8_BAR; PG8_MMA(1, 0, At, B0); PG8_MMA(1, 1, At, B1); PG8_BAR; PG8_SCHED;
;         }
;     ...
;         if (wr == 0) PG8_BAR;
	s_add_i32 s34, s52, s10
	v_lshl_add_u64 v[140:141], v[140:141], 0, s[0:1]
	s_mov_b32 m0, s34
	ds_read_b128 v[188:191], v145 offset:49152
	ds_read_b128 v[192:195], v145 offset:50176
	ds_read_b128 v[216:219], v145 offset:51200
	ds_read_b128 v[220:223], v145 offset:52224
	ds_read_b128 v[224:227], v145 offset:53248
	ds_read_b128 v[228:231], v145 offset:54272
	ds_read_b128 v[232:235], v145 offset:55296
	ds_read_b128 v[236:239], v145 offset:56320
	global_load_lds_dwordx4 v[140:141], off
	s_add_i32 m0, s34, 0x2000
	s_add_u32 s30, s30, 0x40080
	v_lshl_add_u64 v[140:141], v[240:241], 0, s[0:1]
	s_addc_u32 s31, s31, 0
	s_add_i32 s34, s53, s10
	global_load_lds_dwordx4 v[140:141], off
	v_lshl_add_u64 v[140:141], s[30:31], 0, v[0:1]
	s_mov_b32 m0, s34
	s_nop 0
	global_load_lds_dwordx4 v[140:141], off
	v_lshl_add_u64 v[140:141], s[30:31], 0, v[130:131]
	s_add_i32 m0, s34, 0x2000
	s_nop 0
	global_load_lds_dwordx4 v[140:141], off
	v_lshl_add_u64 v[140:141], v[242:243], 0, s[0:1]
	s_mov_b32 m0, s42
	s_nop 0
	global_load_lds_dwordx4 v[140:141], off
	v_lshl_add_u64 v[140:141], v[244:245], 0, s[0:1]
	s_mov_b32 m0, s43
	s_nop 0
	global_load_lds_dwordx4 v[140:141], off
	s_waitcnt vmcnt(8)
	s_waitcnt lgkmcnt(0)
	s_barrier
	s_waitcnt lgkmcnt(0)
	v_mfma_f32_16x16x32_bf16 v[62:65], v[146:149], v[188:191], v[62:65]
	v_mfma_f32_16x16x32_bf16 v[54:57], v[154:157], v[188:191], v[54:57]
	v_mfma_f32_16x16x32_bf16 v[46:49], v[146:149], v[216:219], v[46:49]
	v_mfma_f32_16x16x32_bf16 v[38:41], v[154:157], v[216:219], v[38:41]
	v_mfma_f32_16x16x32_bf16 v[30:33], v[146:149], v[224:227], v[30:33]
	v_mfma_f32_16x16x32_bf16 v[22:25], v[154:157], v[224:227], v[22:25]
	v_mfma_f32_16x16x32_bf16 v[14:17], v[146:149], v[232:235], v[14:17]
	v_mfma_f32_16x16x32_bf16 v[6:9], v[154:157], v[232:235], v[6:9]
	v_mfma_f32_16x16x32_bf16 v[62:65], v[150:153], v[192:195], v[62:65]
	v_mfma_f32_16x16x32_bf16 v[54:57], v[158:161], v[192:195], v[54:57]
	v_mfma_f32_16x16x32_bf16 v[46:49], v[150:153], v[220:223], v[46:49]
	v_mfma_f32_16x16x32_bf16 v[38:41], v[158:161], v[220:223], v[38:41]
	v_mfma_f32_16x16x32_bf16 v[30:33], v[150:153], v[228:231], v[30:33]
	v_mfma_f32_16x16x32_bf16 v[22:25], v[158:161], v[228:231], v[22:25]
	v_mfma_f32_16x16x32_bf16 v[14:17], v[150:153], v[236:239], v[14:17]
	v_mfma_f32_16x16x32_bf16 v[6:9], v[158:161], v[236:239], v[6:9]
	v_mfma_f32_16x16x32_bf16 v[58:61], v[162:165], v[188:191], v[58:61]
	v_mfma_f32_16x16x32_bf16 v[50:53], v[180:183], v[188:191], v[50:53]
	v_mfma_f32_16x16x32_bf16 v[42:45], v[162:165], v[216:219], v[42:45]
	v_mfma_f32_16x16x32_bf16 v[34:37], v[180:183], v[216:219], v[34:37]
	v_mfma_f32_16x16x32_bf16 v[26:29], v[162:165], v[224:227], v[26:29]
	v_mfma_f32_16x16x32_bf16 v[18:21], v[180:183], v[224:227], v[18:21]
	v_mfma_f32_16x16x32_bf16 v[10:13], v[162:165], v[232:235], v[10:13]
	v_mfma_f32_16x16x32_bf16 v[2:5], v[180:183], v[232:235], v[2:5]
	v_mfma_f32_16x16x32_bf16 v[58:61], v[176:179], v[192:195], v[58:61]
	v_mfma_f32_16x16x32_bf16 v[50:53], v[184:187], v[192:195], v[50:53]
	v_mfma_f32_16x16x32_bf16 v[42:45], v[176:179], v[220:223], v[42:45]
	v_mfma_f32_16x16x32_bf16 v[34:37], v[184:187], v[220:223], v[34:37]
	v_mfma_f32_16x16x32_bf16 v[26:29], v[176:179], v[228:231], v[26:29]
	v_mfma_f32_16x16x32_bf16 v[18:21], v[184:187], v[228:231], v[18:21]
	v_mfma_f32_16x16x32_bf16 v[10:13], v[176:179], v[236:239], v[10:13]
	v_mfma_f32_16x16x32_bf16 v[2:5], v[184:187], v[236:239], v[2:5]
	s_barrier
	s_add_i32 s51, s51, 2
	s_add_u32 s22, s22, 0x100
	s_addc_u32 s23, s23, 0
	s_add_u32 s49, s49, 0x100
	s_addc_u32 s50, s50, 0
	s_cmp_gt_u32 s51, 13
	s_cbranch_scc0 .LBB0_921
	s_and_b64 vcc, exec, s[6:7]
	s_cbranch_vccz .LBB0_924
	s_barrier

; #define PG8_STAGE(bufoff, gbase, voff) do { _Pragma("unroll") for (int _i = 0; _i < 2; ++_i) \
;         __builtin_amdgcn_global_load_lds((const unsigned*)((const char*)(gbase) + (voff)[_i]), (LAS unsigned*)(lds + (bufoff) + ldsw + _i * 8192), 16, 0, 0); } while (0)
; #define PG8_LDA(dst, b, h) do { _Pragma("unroll") for (int m = 0; m < 4; ++m) _Pragma("unroll") for (int k = 0; k < 2; ++k) dst[m][k] = *(const LAS bf16x8*)(lds + PG8_SA(b, h) + aoff + m * 2048 + k * 1024); } while (0)
; #define PG8_LDB(dst, b, h) do { _Pragma("unroll") for (int n = 0; n < 2; ++n) _Pragma("unroll") for (int k = 0; k < 2; ++k) dst[n][k] = *(const LAS bf16x8*)(lds + PG8_SB(b, h) + boff + n * 2048 + k * 1024); } while (0)
; #define PG8_MMA(ai, bj, At, Bt) do { __builtin_amdgcn_s_setprio(1); _Pragma("unroll") for (int m = 0; m < 4; ++m) _Pragma("unroll") for (int n = 0; n < 2; ++n) _Pragma("unroll") for (int k = 0; k < 2; ++k) \
;         acc[ai][bj][m][n] = __builtin_amdgcn_mfma_f32_16x16x32_bf16(Bt[n][k], At[m][k], acc[ai][bj][m][n], 0, 0, 0); __builtin_amdgcn_s_setprio(0); } while (0)
; #define PG8_WAIT_V(n) asm volatile("s_waitcnt vmcnt(" #n ")" ::: "memory")
; #define PG8_WAIT_L(n) asm volatile("s_waitcnt lgkmcnt(" #n ")" ::: "memory")
; #define PG8_BAR __builtin_amdgcn_s_barrier()
; #define PG8_SCHED __builtin_amdgcn_sched_barrier(0)
; template <class Epi, bool GS = false>
; __device__ __forceinline__ void gemm_phase(LAS unsigned char* lds, const Gemm g, const StaticOrder& S, const Epi& E, const int tid) {
;     ...
;         for (int t = tg; t < tg + seg; t += 2) {
;             const bool last = (t == nt - 2);
;             const char* a1 = cA + (size_t)(t + 1) * kstep;
;             const char* a2 = last ? nA : cA + (size_t)(t + 2) * kstep; const char* b2 = last ? nB : cB + (size_t)(t + 2) * kstep;
;             const char* a3 = a2 + kstep; const char* b3 = b2 + kstep;
;             PG8_LDB(B0, 0, 0); PG8_LDB(B1, 0, 1); PG8_SCHED; PG8_LDA(At, 0, 0); PG8_STAGE(PG8_SA(1, 1), a1 + hstepA, voffA);
;             PG8_WAIT_V(8); PG8_WAIT_L(0); PG8_BAR; PG8_MMA(0, 0, At, B0); PG8_MMA(0, 1, At, B1); PG8_BAR; PG8_SCHED;
;             PG8_LDA(At, 0, 1); PG8_STAGE(PG8_SB(0, 0), b2, voffB); PG8_STAGE(PG8_SB(0, 1), b2 + hstepB, voffB); PG8_STAGE(PG8_SA(0, 0), a2, voffA);
.LBB0_993:
	s_add_u32 s22, s20, 0x100
	s_addc_u32 s23, s21, 0
	s_add_i32 s53, 0, 0x10000
	s_cmp_eq_u32 s52, 40
	s_cselect_b32 s35, s7, s23
	s_cselect_b32 s34, s6, s22
	v_add_u32_e32 v0, s53, v190
	s_cselect_b32 s31, s17, s51
	s_cselect_b32 s30, s16, s50
	s_add_i32 s54, 0, 0x14000
	ds_read_b128 v[130:133], v0
	ds_read_b128 v[134:137], v0 offset:1024
	ds_read_b128 v[138:141], v0 offset:2048
	ds_read_b128 v[142:145], v0 offset:3072
	v_add_u32_e32 v0, s54, v190
	ds_read_b128 v[146:149], v0
	ds_read_b128 v[150:153], v0 offset:1024
	ds_read_b128 v[154:157], v0 offset:2048
	ds_read_b128 v[158:161], v0 offset:3072
	v_lshl_add_u64 v[188:189], s[20:21], 0, v[176:177]
	s_add_i32 m0, s36, 0xc000
	ds_read_b128 v[180:183], v192
	ds_read_b128 v[184:187], v192 offset:1024
	ds_read_b128 v[216:219], v192 offset:2048
	ds_read_b128 v[220:223], v192 offset:3072
	ds_read_b128 v[224:227], v192 offset:4096
	ds_read_b128 v[228:231], v192 offset:5120
	ds_read_b128 v[232:235], v192 offset:6144
	ds_read_b128 v[236:239], v192 offset:7168
	global_load_lds_dwordx4 v[188:189], off
	v_lshl_add_u64 v[188:189], s[20:21], 0, v[178:179]
	s_add_i32 m0, s36, 0xe000
	s_nop 0
	global_load_lds_dwordx4 v[188:189], off
	s_waitcnt vmcnt(8)
	s_waitcnt lgkmcnt(0)
	s_barrier
	s_waitcnt lgkmcnt(0)
	v_mfma_f32_16x16x32_bf16 v[126:129], v[130:133], v[180:183], v[126:129]
	v_mfma_f32_16x16x32_bf16 v[122:125], v[138:141], v[180:183], v[122:125]
	v_mfma_f32_16x16x32_bf16 v[110:113], v[130:133], v[216:219], v[110:113]
	v_mfma_f32_16x16x32_bf16 v[106:109], v[138:141], v[216:219], v[106:109]
	v_mfma_f32_16x16x32_bf16 v[94:97], v[130:133], v[224:227], v[94:97]
	v_mfma_f32_16x16x32_bf16 v[90:93], v[138:141], v[224:227], v[90:93]
	v_mfma_f32_16x16x32_bf16 v[78:81], v[130:133], v[232:235], v[78:81]
	v_mfma_f32_16x16x32_bf16 v[74:77], v[138:141], v[232:235], v[74:77]
	v_mfma_f32_16x16x32_bf16 v[126:129], v[134:137], v[184:187], v[126:129]
	v_mfma_f32_16x16x32_bf16 v[122:125], v[142:145], v[184:187], v[122:125]
	v_mfma_f32_16x16x32_bf16 v[110:113], v[134:137], v[220:223], v[110:113]
	v_mfma_f32_16x16x32_bf16 v[106:109], v[142:145], v[220:223], v[106:109]
	v_mfma_f32_16x16x32_bf16 v[94:97], v[134:137], v[228:231], v[94:97]
	v_mfma_f32_16x16x32_bf16 v[90:93], v[142:145], v[228:231], v[90:93]
	v_mfma_f32_16x16x32_bf16 v[78:81], v[134:137], v[236:239], v[78:81]
	v_mfma_f32_16x16x32_bf16 v[74:77], v[142:145], v[236:239], v[74:77]
	v_mfma_f32_16x16x32_bf16 v[118:121], v[146:149], v[180:183], v[118:121]
	v_mfma_f32_16x16x32_bf16 v[114:117], v[154:157], v[180:183], v[114:117]
	v_mfma_f32_16x16x32_bf16 v[102:105], v[146:149], v[216:219], v[102:105]
	v_mfma_f32_16x16x32_bf16 v[98:101], v[154:157], v[216:219], v[98:101]
	v_mfma_f32_16x16x32_bf16 v[86:89], v[146:149], v[224:227], v[86:89]
	v_mfma_f32_16x16x32_bf16 v[82:85], v[154:157], v[224:227], v[82:85]
	v_mfma_f32_16x16x32_bf16 v[70:73], v[146:149], v[232:235], v[70:73]
	v_mfma_f32_16x16x32_bf16 v[66:69], v[154:157], v[232:235], v[66:69]
	v_mfma_f32_16x16x32_bf16 v[118:121], v[150:153], v[184:187], v[118:121]
	v_mfma_f32_16x16x32_bf16 v[114:117], v[158:161], v[184:187], v[114:117]
	v_mfma_f32_16x16x32_bf16 v[102:105], v[150:153], v[220:223], v[102:105]
	v_mfma_f32_16x16x32_bf16 v[98:101], v[158:161], v[220:223], v[98:101]
	v_mfma_f32_16x16x32_bf16 v[86:89], v[150:153], v[228:231], v[86:89]
	v_mfma_f32_16x16x32_bf16 v[82:85], v[158:161], v[228:231], v[82:85]
	v_mfma_f32_16x16x32_bf16 v[70:73], v[150:153], v[236:239], v[70:73]
	v_mfma_f32_16x16x32_bf16 v[66:69], v[158:161], v[236:239], v[66:69]
	s_barrier
	s_add_i32 s20, s53, s10
	v_lshl_add_u64 v[188:189], s[30:31], 0, v[164:165]
	s_mov_b32 m0, s20
	ds_read_b128 v[180:183], v192 offset:16384
	ds_read_b128 v[184:187], v192 offset:17408
	ds_read_b128 v[216:219], v192 offset:18432
	ds_read_b128 v[220:223], v192 offset:19456
	ds_read_b128 v[224:227], v192 offset:20480
	ds_read_b128 v[228:231], v192 offset:21504
	ds_read_b128 v[232:235], v192 offset:22528
	ds_read_b128 v[236:239], v192 offset:23552
	global_load_lds_dwordx4 v[188:189], off
	s_add_i32 m0, s20, 0x2000
	s_add_u32 s20, s30, 0xb0000
	v_lshl_add_u64 v[194:195], s[30:31], 0, v[162:163]
	s_addc_u32 s21, s31, 0
	s_add_i32 s53, s54, s10
	global_load_lds_dwordx4 v[194:195], off
	v_lshl_add_u64 v[240:241], s[20:21], 0, v[164:165]
	s_mov_b32 m0, s53
	v_lshl_add_u64 v[242:243], s[34:35], 0, v[162:163]
	global_load_lds_dwordx4 v[240:241], off
	v_lshl_add_u64 v[240:241], s[20:21], 0, v[162:163]
	s_add_i32 m0, s53, 0x2000
	s_nop 0
	global_load_lds_dwordx4 v[240:241], off
	v_lshl_add_u64 v[240:241], s[34:35], 0, v[164:165]
	s_mov_b32 m0, s36
	s_nop 0
	global_load_lds_dwordx4 v[240:241], off
	s_mov_b32 m0, s37
	s_nop 0
	global_load_lds_dwordx4 v[242:243], off
	s_waitcnt vmcnt(8)
	s_waitcnt lgkmcnt(0)
	s_barrier
; #define PG8_STAGE(bufoff, gbase, voff) do { _Pragma("unroll") for (int _i = 0; _i < 2; ++_i) \
;         __builtin_amdgcn_global_load_lds((const unsigned*)((const char*)(gbase) + (voff)[_i]), (LAS unsigned*)(lds + (bufoff) + ldsw + _i * 8192), 16, 0, 0); } while (0)
; #define PG8_LDA(dst, b, h) do { _Pragma("unroll") for (int m = 0; m < 4; ++m) _Pragma("unroll") for (int k = 0; k < 2; ++k) dst[m][k] = *(const LAS bf16x8*)(lds + PG8_SA(b, h) + aoff + m * 2048 + k * 1024); } while (0)
; #define PG8_LDB(dst, b, h) do { _Pragma("unroll") for (int n = 0; n < 2; ++n) _Pragma("unroll") for (int k = 0; k < 2; ++k) dst[n][k] = *(const LAS bf16x8*)(lds + PG8_SB(b, h) + boff + n * 2048 + k * 1024); } while (0)
; #define PG8_MMA(ai, bj, At, Bt) do { __builtin_amdgcn_s_setprio(1); _Pragma("unroll") for (int m = 0; m < 4; ++m) _Pragma("unroll") for (int n = 0; n < 2; ++n) _Pragma("unroll") for (int k = 0; k < 2; ++k) \
;         acc[ai][bj][m][n] = __builtin_amdgcn_mfma_f32_16x16x32_bf16(Bt[n][k], At[m][k], acc[ai][bj][m][n], 0, 0, 0); __builtin_amdgcn_s_setprio(0); } while (0)
; #define PG8_WAIT_V(n) asm volatile("s_waitcnt vmcnt(" #n ")" ::: "memory")
; #define PG8_WAIT_L(n) asm volatile("s_waitcnt lgkmcnt(" #n ")" ::: "memory")
; #define PG8_BAR __builtin_amdgcn_s_barrier()
; #define PG8_SCHED __builtin_amdgcn_sched_barrier(0)
; template <class Epi, bool GS = false>
; __device__ __forceinline__ void gemm_phase(LAS unsigned char* lds, const Gemm g, const StaticOrder& S, const Epi& E, const int tid) {
;     ...
;             PG8_WAIT_V(8); PG8_WAIT_L(0); PG8_BAR; PG8_MMA(1, 0, At, B0); PG8_MMA(1, 1, At, B1); PG8_BAR; PG8_SCHED;
;             PG8_LDB(B0, 1, 0); PG8_LDB(B1, 1, 1); PG8_SCHED; PG8_LDA(At, 1, 0); PG8_STAGE(PG8_SA(0, 1), a2 + hstepA, voffA);
;             PG8_WAIT_V(8); PG8_WAIT_L(0); PG8_BAR; PG8_MMA(0, 0, At, B0); PG8_MMA(0, 1, At, B1); PG8_BAR; PG8_SCHED;
;             PG8_LDA(At, 1, 1); PG8_STAGE(PG8_SB(1, 0), b3, voffB); PG8_STAGE(PG8_SB(1, 1), b3 + hstepB, voffB); PG8_STAGE(PG8_SA(1, 0), a3, voffA);
;             PG8_WAIT_V(8); PG8_WAIT_L(0); PG8_BAR; PG8_MMA(1, 0, At, B0); PG8_MMA(1, 1, At, B1); PG8_BAR; PG8_SCHED;
	s_waitcnt lgkmcnt(0)
	v_mfma_f32_16x16x32_bf16 v[62:65], v[130:133], v[180:183], v[62:65]
	v_mfma_f32_16x16x32_bf16 v[58:61], v[138:141], v[180:183], v[58:61]
	v_mfma_f32_16x16x32_bf16 v[46:49], v[130:133], v[216:219], v[46:49]
	v_mfma_f32_16x16x32_bf16 v[42:45], v[138:141], v[216:219], v[42:45]
	v_mfma_f32_16x16x32_bf16 v[30:33], v[130:133], v[224:227], v[30:33]
	v_mfma_f32_16x16x32_bf16 v[26:29], v[138:141], v[224:227], v[26:29]
	v_mfma_f32_16x16x32_bf16 v[14:17], v[130:133], v[232:235], v[14:17]
	v_mfma_f32_16x16x32_bf16 v[10:13], v[138:141], v[232:235], v[10:13]
	v_mfma_f32_16x16x32_bf16 v[62:65], v[134:137], v[184:187], v[62:65]
	v_mfma_f32_16x16x32_bf16 v[58:61], v[142:145], v[184:187], v[58:61]
	v_mfma_f32_16x16x32_bf16 v[46:49], v[134:137], v[220:223], v[46:49]
	v_mfma_f32_16x16x32_bf16 v[42:45], v[142:145], v[220:223], v[42:45]
	v_mfma_f32_16x16x32_bf16 v[30:33], v[134:137], v[228:231], v[30:33]
	v_mfma_f32_16x16x32_bf16 v[26:29], v[142:145], v[228:231], v[26:29]
	v_mfma_f32_16x16x32_bf16 v[14:17], v[134:137], v[236:239], v[14:17]
	v_mfma_f32_16x16x32_bf16 v[10:13], v[142:145], v[236:239], v[10:13]
	v_mfma_f32_16x16x32_bf16 v[54:57], v[146:149], v[180:183], v[54:57]
	v_mfma_f32_16x16x32_bf16 v[50:53], v[154:157], v[180:183], v[50:53]
	v_mfma_f32_16x16x32_bf16 v[38:41], v[146:149], v[216:219], v[38:41]
	v_mfma_f32_16x16x32_bf16 v[34:37], v[154:157], v[216:219], v[34:37]
	v_mfma_f32_16x16x32_bf16 v[22:25], v[146:149], v[224:227], v[22:25]
	v_mfma_f32_16x16x32_bf16 v[18:21], v[154:157], v[224:227], v[18:21]
	v_mfma_f32_16x16x32_bf16 v[6:9], v[146:149], v[232:235], v[6:9]
	v_mfma_f32_16x16x32_bf16 v[2:5], v[154:157], v[232:235], v[2:5]
	v_mfma_f32_16x16x32_bf16 v[54:57], v[150:153], v[184:187], v[54:57]
	v_mfma_f32_16x16x32_bf16 v[50:53], v[158:161], v[184:187], v[50:53]
	v_mfma_f32_16x16x32_bf16 v[38:41], v[150:153], v[220:223], v[38:41]
	v_mfma_f32_16x16x32_bf16 v[34:37], v[158:161], v[220:223], v[34:37]
	v_mfma_f32_16x16x32_bf16 v[22:25], v[150:153], v[228:231], v[22:25]
	v_mfma_f32_16x16x32_bf16 v[18:21], v[158:161], v[228:231], v[18:21]
	v_mfma_f32_16x16x32_bf16 v[6:9], v[150:153], v[236:239], v[6:9]
	v_mfma_f32_16x16x32_bf16 v[2:5], v[158:161], v[236:239], v[2:5]
	s_barrier
	s_add_i32 s53, 0, 0x18000
	v_add_u32_e32 v0, s53, v190
	s_add_i32 s54, 0, 0x1c000
	ds_read_b128 v[130:133], v0
	ds_read_b128 v[134:137], v0 offset:1024
	ds_read_b128 v[138:141], v0 offset:2048
	ds_read_b128 v[142:145], v0 offset:3072
	v_add_u32_e32 v0, s54, v190
	ds_read_b128 v[146:149], v0
	ds_read_b128 v[150:153], v0 offset:1024
	ds_read_b128 v[154:157], v0 offset:2048
	ds_read_b128 v[158:161], v0 offset:3072
	s_add_u32 s20, s34, 0xb0000
	s_addc_u32 s21, s35, 0
	s_mov_b32 m0, s38
	v_lshl_add_u64 v[244:245], s[20:21], 0, v[164:165]
	ds_read_b128 v[180:183], v192 offset:32768
	ds_read_b128 v[184:187], v192 offset:33792
	ds_read_b128 v[216:219], v192 offset:34816
	ds_read_b128 v[220:223], v192 offset:35840
	ds_read_b128 v[224:227], v192 offset:36864
	ds_read_b128 v[228:231], v192 offset:37888
	ds_read_b128 v[232:235], v192 offset:38912
	ds_read_b128 v[236:239], v192 offset:39936
	global_load_lds_dwordx4 v[244:245], off
	v_lshl_add_u64 v[244:245], s[20:21], 0, v[162:163]
	s_mov_b32 m0, s39
	s_nop 0
	global_load_lds_dwordx4 v[244:245], off
	s_waitcnt vmcnt(8)
	s_waitcnt lgkmcnt(0)
	s_barrier
	s_waitcnt lgkmcnt(0)
	v_mfma_f32_16x16x32_bf16 v[126:129], v[130:133], v[180:183], v[126:129]
	v_mfma_f32_16x16x32_bf16 v[122:125], v[138:141], v[180:183], v[122:125]
	v_mfma_f32_16x16x32_bf16 v[110:113], v[130:133], v[216:219], v[110:113]
	v_mfma_f32_16x16x32_bf16 v[106:109], v[138:141], v[216:219], v[106:109]
	v_mfma_f32_16x16x32_bf16 v[94:97], v[130:133], v[224:227], v[94:97]
	v_mfma_f32_16x16x32_bf16 v[90:93], v[138:141], v[224:227], v[90:93]
	v_mfma_f32_16x16x32_bf16 v[78:81], v[130:133], v[232:235], v[78:81]
	v_mfma_f32_16x16x32_bf16 v[74:77], v[138:141], v[232:235], v[74:77]
	v_mfma_f32_16x16x32_bf16 v[126:129], v[134:137], v[184:187], v[126:129]
	v_mfma_f32_16x16x32_bf16 v[122:125], v[142:145], v[184:187], v[122:125]
	v_mfma_f32_16x16x32_bf16 v[110:113], v[134:137], v[220:223], v[110:113]
	v_mfma_f32_16x16x32_bf16 v[106:109], v[142:145], v[220:223], v[106:109]
	v_mfma_f32_16x16x32_bf16 v[94:97], v[134:137], v[228:231], v[94:97]
	v_mfma_f32_16x16x32_bf16 v[90:93], v[142:145], v[228:231], v[90:93]
	v_mfma_f32_16x16x32_bf16 v[78:81], v[134:137], v[236:239], v[78:81]
	v_mfma_f32_16x16x32_bf16 v[74:77], v[142:145], v[236:239], v[74:77]
	v_mfma_f32_16x16x32_bf16 v[118:121], v[146:149], v[180:183], v[118:121]
	v_mfma_f32_16x16x32_bf16 v[114:117], v[154:157], v[180:183], v[114:117]
	v_mfma_f32_16x16x32_bf16 v[102:105], v[146:149], v[216:219], v[102:105]
	v_mfma_f32_16x16x32_bf16 v[98:101], v[154:157], v[216:219], v[98:101]
	v_mfma_f32_16x16x32_bf16 v[86:89], v[146:149], v[224:227], v[86:89]
	v_mfma_f32_16x16x32_bf16 v[82:85], v[154:157], v[224:227], v[82:85]
	v_mfma_f32_16x16x32_bf16 v[70:73], v[146:149], v[232:235], v[70:73]
	v_mfma_f32_16x16x32_bf16 v[66:69], v[154:157], v[232:235], v[66:69]
	v_mfma_f32_16x16x32_bf16 v[118:121], v[150:153], v[184:187], v[118:121]
	v_mfma_f32_16x16x32_bf16 v[114:117], v[158:161], v[184:187], v[114:117]
	v_mfma_f32_16x16x32_bf16 v[102:105], v[150:153], v[220:223], v[102:105]
	v_mfma_f32_16x16x32_bf16 v[98:101], v[158:161], v[220:223], v[98:101]
	v_mfma_f32_16x16x32_bf16 v[86:89], v[150:153], v[228:231], v[86:89]
	v_mfma_f32_16x16x32_bf16 v[82:85], v[158:161], v[228:231], v[82:85]
	v_mfma_f32_16x16x32_bf16 v[70:73], v[150:153], v[236:239], v[70:73]
	v_mfma_f32_16x16x32_bf16 v[66:69], v[158:161], v[236:239], v[66:69]
	s_barrier
; #define PG8_STAGE(bufoff, gbase, voff) do { _Pragma("unroll") for (int _i = 0; _i < 2; ++_i) \
;         __builtin_amdgcn_global_load_lds((const unsigned*)((const char*)(gbase) + (voff)[_i]), (LAS unsigned*)(lds + (bufoff) + ldsw + _i * 8192), 16, 0, 0); } while (0)
; #define PG8_LDA(dst, b, h) do { _Pragma("unroll") for (int m = 0; m < 4; ++m) _Pragma("unroll") for (int k = 0; k < 2; ++k) dst[m][k] = *(const LAS bf16x8*)(lds + PG8_SA(b, h) + aoff + m * 2048 + k * 1024); } while (0)
; #define PG8_LDB(dst, b, h) do { _Pragma("unroll") for (int n = 0; n < 2; ++n) _Pragma("unroll") for (int k = 0; k < 2; ++k) dst[n][k] = *(const LAS bf16x8*)(lds + PG8_SB(b, h) + boff + n * 2048 + k * 1024); } while (0)
; #define PG8_MMA(ai, bj, At, Bt) do { __builtin_amdgcn_s_setprio(1); _Pragma("unroll") for (int m = 0; m < 4; ++m) _Pragma("unroll") for (int n = 0; n < 2; ++n) _Pragma("unroll") for (int k = 0; k < 2; ++k) \
;         acc[ai][bj][m][n] = __builtin_amdgcn_mfma_f32_16x16x32_bf16(Bt[n][k], At[m][k], acc[ai][bj][m][n], 0, 0, 0); __builtin_amdgcn_s_setprio(0); } while (0)
; #define PG8_WAIT_V(n) asm volatile("s_waitcnt vmcnt(" #n ")" ::: "memory")
; #define PG8_WAIT_L(n) asm volatile("s_waitcnt lgkmcnt(" #n ")" ::: "memory")
; #define PG8_BAR __builtin_amdgcn_s_barrier()
; #define PG8_SCHED __builtin_amdgcn_sched_barrier(0)
; template <class Epi, bool GS = false>
; __device__ __forceinline__ void gemm_phase(LAS unsigned char* lds, const Gemm g, const StaticOrder& S, const Epi& E, const int tid) {
;     ...
;             PG8_LDB(B0, 1, 0); PG8_LDB(B1, 1, 1); PG8_SCHED; PG8_LDA(At, 1, 0); PG8_STAGE(PG8_SA(0, 1), a2 + hstepA, voffA);
;             PG8_WAIT_V(8); PG8_WAIT_L(0); PG8_BAR; PG8_MMA(0, 0, At, B0); PG8_MMA(0, 1, At, B1); PG8_BAR; PG8_SCHED;
;             PG8_LDA(At, 1, 1); PG8_STAGE(PG8_SB(1, 0), b3, voffB); PG8_STAGE(PG8_SB(1, 1), b3 + hstepB, voffB); PG8_STAGE(PG8_SA(1, 0), a3, voffA);
;             PG8_WAIT_V(8); PG8_WAIT_L(0); PG8_BAR; PG8_MMA(1, 0, At, B0); PG8_MMA(1, 1, At, B1); PG8_BAR; PG8_SCHED;
;         }
;     ...
;         if (wr == 0) PG8_BAR;
	s_add_i32 s20, s53, s10
	v_lshl_add_u64 v[188:189], v[188:189], 0, s[0:1]
	s_mov_b32 m0, s20
	ds_read_b128 v[180:183], v192 offset:49152
	ds_read_b128 v[184:187], v192 offset:50176
	ds_read_b128 v[216:219], v192 offset:51200
	ds_read_b128 v[220:223], v192 offset:52224
	ds_read_b128 v[224:227], v192 offset:53248
	ds_read_b128 v[228:231], v192 offset:54272
	ds_read_b128 v[232:235], v192 offset:55296
	ds_read_b128 v[236:239], v192 offset:56320
	global_load_lds_dwordx4 v[188:189], off
	s_add_i32 m0, s20, 0x2000
	s_add_u32 s20, s30, 0xb0080
	v_lshl_add_u64 v[188:189], v[194:195], 0, s[0:1]
	s_addc_u32 s21, s31, 0
	s_add_i32 s30, s54, s10
	global_load_lds_dwordx4 v[188:189], off
	v_lshl_add_u64 v[188:189], s[20:21], 0, v[164:165]
	s_mov_b32 m0, s30
	s_nop 0
	global_load_lds_dwordx4 v[188:189], off
	v_lshl_add_u64 v[188:189], s[20:21], 0, v[162:163]
	s_add_i32 m0, s30, 0x2000
	s_nop 0
	global_load_lds_dwordx4 v[188:189], off
	v_lshl_add_u64 v[188:189], v[240:241], 0, s[0:1]
	s_mov_b32 m0, s43
	s_nop 0
	global_load_lds_dwordx4 v[188:189], off
	v_lshl_add_u64 v[188:189], v[242:243], 0, s[0:1]
	s_mov_b32 m0, s44
	s_nop 0
	global_load_lds_dwordx4 v[188:189], off
	s_waitcnt vmcnt(8)
	s_waitcnt lgkmcnt(0)
	s_barrier
	s_waitcnt lgkmcnt(0)
	v_mfma_f32_16x16x32_bf16 v[62:65], v[130:133], v[180:183], v[62:65]
	v_mfma_f32_16x16x32_bf16 v[58:61], v[138:141], v[180:183], v[58:61]
	v_mfma_f32_16x16x32_bf16 v[46:49], v[130:133], v[216:219], v[46:49]
	v_mfma_f32_16x16x32_bf16 v[42:45], v[138:141], v[216:219], v[42:45]
	v_mfma_f32_16x16x32_bf16 v[30:33], v[130:133], v[224:227], v[30:33]
	v_mfma_f32_16x16x32_bf16 v[26:29], v[138:141], v[224:227], v[26:29]
	v_mfma_f32_16x16x32_bf16 v[14:17], v[130:133], v[232:235], v[14:17]
	v_mfma_f32_16x16x32_bf16 v[10:13], v[138:141], v[232:235], v[10:13]
	v_mfma_f32_16x16x32_bf16 v[62:65], v[134:137], v[184:187], v[62:65]
	v_mfma_f32_16x16x32_bf16 v[58:61], v[142:145], v[184:187], v[58:61]
	v_mfma_f32_16x16x32_bf16 v[46:49], v[134:137], v[220:223], v[46:49]
	v_mfma_f32_16x16x32_bf16 v[42:45], v[142:145], v[220:223], v[42:45]
	v_mfma_f32_16x16x32_bf16 v[30:33], v[134:137], v[228:231], v[30:33]
	v_mfma_f32_16x16x32_bf16 v[26:29], v[142:145], v[228:231], v[26:29]
	v_mfma_f32_16x16x32_bf16 v[14:17], v[134:137], v[236:239], v[14:17]
	v_mfma_f32_16x16x32_bf16 v[10:13], v[142:145], v[236:239], v[10:13]
	v_mfma_f32_16x16x32_bf16 v[54:57], v[146:149], v[180:183], v[54:57]
	v_mfma_f32_16x16x32_bf16 v[50:53], v[154:157], v[180:183], v[50:53]
	v_mfma_f32_16x16x32_bf16 v[38:41], v[146:149], v[216:219], v[38:41]
	v_mfma_f32_16x16x32_bf16 v[34:37], v[154:157], v[216:219], v[34:37]
	v_mfma_f32_16x16x32_bf16 v[22:25], v[146:149], v[224:227], v[22:25]
	v_mfma_f32_16x16x32_bf16 v[18:21], v[154:157], v[224:227], v[18:21]
	v_mfma_f32_16x16x32_bf16 v[6:9], v[146:149], v[232:235], v[6:9]
	v_mfma_f32_16x16x32_bf16 v[2:5], v[154:157], v[232:235], v[2:5]
	v_mfma_f32_16x16x32_bf16 v[54:57], v[150:153], v[184:187], v[54:57]
	v_mfma_f32_16x16x32_bf16 v[50:53], v[158:161], v[184:187], v[50:53]
	v_mfma_f32_16x16x32_bf16 v[38:41], v[150:153], v[220:223], v[38:41]
	v_mfma_f32_16x16x32_bf16 v[34:37], v[158:161], v[220:223], v[34:37]
	v_mfma_f32_16x16x32_bf16 v[22:25], v[150:153], v[228:231], v[22:25]
	v_mfma_f32_16x16x32_bf16 v[18:21], v[158:161], v[228:231], v[18:21]
	v_mfma_f32_16x16x32_bf16 v[6:9], v[150:153], v[236:239], v[6:9]
	v_mfma_f32_16x16x32_bf16 v[2:5], v[158:161], v[236:239], v[2:5]
	s_barrier
	s_add_i32 s52, s52, 2
	s_add_u32 s50, s50, 0x100
	s_addc_u32 s51, s51, 0
	s_cmp_gt_u32 s52, 41
	s_mov_b64 s[20:21], s[22:23]
	s_cbranch_scc0 .LBB0_993
	s_and_b64 vcc, exec, s[14:15]
	s_cbranch_vccz .LBB0_996
	s_barrier
